# P3 gate hooks: add+clamp+mul(-log2e) folded to fma+clamp with pre-scaled biases and scaled clamp bounds (384 fewer VALU per wave-unit)
# speedup vs baseline: 1.0043x; 1.0043x over previous
; #define PG8_STAGE(bufoff, gbase, voff) do { _Pragma("unroll") for (int _i = 0; _i < 2; ++_i) \
;         __builtin_amdgcn_global_load_lds((const unsigned*)((const char*)(gbase) + (voff)[_i]), (PG8_LAS unsigned*)(lds + (bufoff) + ldsw + _i * 8192), 16, 0, 0); } while (0)
; #define PG8_WAIT_V(n) asm volatile("s_waitcnt vmcnt(" #n ")" ::: "memory")
; #define PG8_BAR __builtin_amdgcn_s_barrier()
; template <class Epi, class Sched, bool ALIGN_EPI = false, bool SP2 = false>
; __device__ __forceinline__ void gemm_phase(PG8_LAS unsigned char* lds, const Gemm g, const Sched& S, const Epi& E) {
;     ...
;         PG8_STAGE(PG8_SB(0, 0), cB, voffB); PG8_STAGE(PG8_SB(0, 1), cB + hstepB, voffB); PG8_STAGE(PG8_SA(0, 0), cA, voffA); PG8_STAGE(PG8_SA(0, 1), cA + hstep, voffA);
;         if (wr == 1) PG8_BAR;
;         PG8_WAIT_V(2); PG8_BAR;
;         PG8_STAGE(PG8_SB(1, 0), cB + kstep, voffB); PG8_STAGE(PG8_SA(1, 0), cA + kstep, voffA); PG8_STAGE(PG8_SB(1, 1), cB + hstepB + kstep, voffB);
;         PG8_WAIT_V(6); PG8_BAR;
.LBB0_370:
	s_and_b32 s80, s5, 3
	s_lshl_b32 s8, s1, 6
	s_lshl_b32 s5, s1, 13
	s_lshl_b32 s14, s80, 12
	s_add_u32 s12, s46, 0x8000
	s_addc_u32 s13, s47, 0
	s_add_i32 m0, s74, 0x18000
	v_lshl_add_u64 v[8:9], s[12:13], 0, v[200:201]
	s_waitcnt vmcnt(2)
	s_barrier
	global_load_lds_dwordx4 v[8:9], off
	s_add_i32 m0, s74, 0x1a000
	v_lshl_add_u64 v[8:9], s[12:13], 0, v[204:205]
	s_add_u32 s12, s28, 0x8000
	s_addc_u32 s13, s29, 0
	s_add_i32 s81, s74, 0x8000
	global_load_lds_dwordx4 v[8:9], off
	s_mov_b32 m0, s81
	s_add_i32 s82, s74, 0xa000
	global_load_lds_dwordx4 v198, s[12:13]
	v_lshl_add_u64 v[8:9], s[12:13], 0, v[202:203]
	s_add_u32 s12, s46, 0x9000
	s_mov_b32 m0, s82
	s_addc_u32 s13, s47, 0
	global_load_lds_dwordx4 v[8:9], off
	s_add_i32 m0, s74, 0x1c000
	s_nop 0
	global_load_lds_dwordx4 v200, s[12:13]
	s_add_i32 m0, s74, 0x1e000
	v_lshlrev_b32_e32 v10, 2, v218
	global_load_lds_dwordx4 v204, s[12:13]
	v_bfe_u32 v9, v218, 4, 2
	v_and_b32_e32 v8, 15, v218
	v_lshlrev_b32_e32 v220, 4, v9
	v_lshlrev_b32_e32 v219, 3, v9
	v_lshl_or_b32 v9, v8, 6, v220
	v_and_b32_e32 v10, 32, v10
	s_lshl_b32 s1, s1, 2
	s_sext_i32_i8 s27, s4
	v_bitop3_b32 v11, v9, s5, v10 bitop3:0xde
	v_lshlrev_b32_e32 v9, 6, v218
	s_movk_i32 s4, 0x3c0
	s_or_b32 s1, s1, s80
	s_lshl_b64 s[12:13], s[8:9], 7
	v_and_or_b32 v9, v9, s4, v220
	s_cmpk_lt_u32 s0, 0x100
	v_bitop3_b32 v221, s14, v9, v10 bitop3:0xf6
	s_cselect_b64 s[14:15], -1, 0
	s_ashr_i32 s8, s33, 31
	s_add_u32 s0, s38, s12
	s_mul_i32 s4, s1, 0x900
	v_lshlrev_b32_e32 v206, 4, v1
	v_mov_b32_e32 v207, v2
	s_addc_u32 s1, s39, s13
	v_lshl_add_u64 v[208:209], s[0:1], 0, v[206:207]
	s_add_i32 s0, s4, 0
	v_and_b32_e32 v222, 0x70, v5
	s_add_i32 s0, s0, 0x20000
	v_and_b32_e32 v5, 0x3800, v5
	v_lshlrev_b32_e32 v6, 7, v6
	s_movk_i32 s1, 0x90
	v_mov_b32_e32 v10, s0
	v_or3_b32 v5, v3, v5, v6
	v_mad_u32_u24 v223, v8, s1, v10
	v_add_u32_e32 v8, v5, v4
	v_and_b32_e32 v5, 0x7800, v7
	s_waitcnt vmcnt(6)
	v_lshrrev_b32_e32 v9, 3, v1
	v_or3_b32 v3, v3, v5, v6
	v_mad_u32_u24 v224, v9, s1, v10
	s_add_u32 s16, s42, 0x1000
	v_mov_b32_e32 v9, v2
	s_mov_b64 s[0:1], 0xc000
	v_add_u32_e32 v4, v3, v4
	v_mov_b32_e32 v5, v2
	s_addc_u32 s17, s43, 0
	v_lshl_add_u64 v[210:211], v[8:9], 0, s[0:1]
	v_lshl_add_u64 v[212:213], v[4:5], 0, s[0:1]
	v_mov_b64_e32 v[214:215], 0x400
	v_mov_b64_e32 v[216:217], 0x3ff
	s_movk_i32 s83, 0x44
	s_movk_i32 s84, 0x1000
	s_mov_b32 s85, 0xc22d1f97
	s_mov_b32 s89, 0xbfb8aa3b
	s_movk_i32 s86, 0x5000
	s_add_i32 s87, 0, 0x10000
	s_add_i32 s88, 0, 0x14000
	v_add_u32_e32 v225, 0, v11
	v_mov_b32_e32 v226, 0x422d1f97
	s_barrier
	s_branch .LBB0_373

; __device__ __forceinline__ size_t tm_block(int pm, int ct, int nct) { return ((size_t)pm * nct + ct) * 32768; }
; #define UNPK0(q_) ((f32x4){bf_lo((q_).x), bf_hi((q_).x), bf_lo((q_).y), bf_hi((q_).y)})
; #define UNPK1(q_) ((f32x4){bf_lo((q_).z), bf_hi((q_).z), bf_lo((q_).w), bf_hi((q_).w)})
;     static __device__ __forceinline__ float eneg(float g) { return __builtin_amdgcn_exp2f(-1.4426950408889634f * fminf(fmaxf(g, -30.f), 30.f)); }
;     __device__ __forceinline__ void mid(f32x4 (&acc)[2][2][4][2], const Unit& u, int wr, int wc, int fr, int fq) const {
;     ...
;         const PieceIn pa(scr, Z, tm_block(pm, ga_ct + cb, znct), wr, wc, fr, fq), pb(scr, Z, tm_block(pm, gb_ct + cb, znct), wr, wc, fr, fq);
;         const int col0 = cb * 64 + 8 * fq;
;         f32x4 ba[2][2], bb[2][2];
; #pragma unroll
;         for (int bj = 0; bj < 2; ++bj) { ba[bj][0] = *(const f32x4*)(bg + col0 + bj * 32); ba[bj][1] = *(const f32x4*)(bg + col0 + bj * 32 + 4); bb[bj][0] = *(const f32x4*)(bg + 1024 + col0 + bj * 32); bb[bj][1] = *(const f32x4*)(bg + 1024 + col0 + bj * 32 + 4); }
; #pragma unroll
;         for (int am = 0; am < 4; ++am) { const int ai = am >> 1;
;             u32x4 ra[4][2], rb[4][2];
; #pragma unroll
;             for (int m = 2 * (am & 1); m < 2 * (am & 1) + 2; ++m) { pa.fetch(ai, m, ra[m][0], ra[m][1]); pb.fetch(ai, m, rb[m][0], rb[m][1]); }
;             asm volatile("" ::: "memory");
; #pragma unroll
;             for (int m = 2 * (am & 1); m < 2 * (am & 1) + 2; ++m) {
;                 pa.stage(ra[m][0], ra[m][1]); const u32x4 ga0 = pa.get(0), ga1 = pa.get(1);
;                 asm volatile("" ::: "memory");
;                 pb.stage(rb[m][0], rb[m][1]); const u32x4 gb0 = pb.get(0), gb1 = pb.get(1);
;                 asm volatile("" ::: "memory");
; #pragma unroll
;                 for (int bj = 0; bj < 2; ++bj) { const u32x4 ga = bj ? ga1 : ga0, gb = bj ? gb1 : gb0;
;                     const f32x4 a0 = UNPK0(ga) + ba[bj][0], a1 = UNPK1(ga) + ba[bj][1], b0 = UNPK0(gb) + bb[bj][0], b1 = UNPK1(gb) + bb[bj][1];
; #pragma unroll
;                     for (int k = 0; k < 4; ++k) { acc[ai][bj][m][0][k] *= (1.0f + eneg(b0[k])) * __builtin_amdgcn_rcpf(1.0f + eneg(a0[k]));
.LBB0_381:
	s_cmp_lg_u32 s46, 0x40000
	s_cbranch_scc1 .LBB0_380
	v_mov_b32_e32 v3, s26
	v_mov_b32_e32 v136, s44
	v_add_u32_e32 v188, v223, v220
	v_add_u32_e32 v4, 36, v136
	v_ashrrev_i32_e32 v5, 31, v4
	v_mad_i64_i32 v[4:5], s[48:49], v3, s83, v[4:5]
	v_add_u32_e32 v134, 52, v136
	v_ashrrev_i32_e32 v135, 31, v134
	v_lshlrev_b64 v[4:5], 15, v[4:5]
	v_lshl_add_u64 v[186:187], v[208:209], 0, v[4:5]
	v_mad_i64_i32 v[4:5], s[48:49], v3, s83, v[134:135]
	global_load_dwordx4 v[190:193], v[186:187], off
	global_load_dwordx4 v[194:197], v[186:187], off offset:1024
	v_lshlrev_b64 v[4:5], 15, v[4:5]
	v_lshl_add_u64 v[4:5], v[208:209], 0, v[4:5]
	global_load_dwordx4 v[228:231], v[4:5], off
	global_load_dwordx4 v[232:235], v[4:5], off offset:1024
	v_lshl_or_b32 v134, v136, 6, v219
	v_ashrrev_i32_e32 v135, 31, v134
	v_lshlrev_b64 v[134:135], 2, v[134:135]
	v_lshl_add_u64 v[138:139], s[42:43], 0, v[134:135]
	v_add_co_u32_e32 v166, vcc, s84, v138
	v_lshl_add_u64 v[140:141], s[16:17], 0, v[134:135]
	global_load_dwordx4 v[150:153], v[138:139], off offset:16
	global_load_dwordx4 v[158:161], v[138:139], off
	global_load_dwordx4 v[162:165], v[140:141], off
	v_addc_co_u32_e32 v167, vcc, 0, v139, vcc
	global_load_dwordx4 v[154:157], v[166:167], off offset:16
	global_load_dwordx4 v[134:137], v[138:139], off offset:144
	global_load_dwordx4 v[142:145], v[138:139], off offset:128
	global_load_dwordx4 v[146:149], v[140:141], off offset:128
	s_nop 0
	global_load_dwordx4 v[138:141], v[166:167], off offset:144
	global_load_dwordx4 v[174:177], v[186:187], off offset:2048
	global_load_dwordx4 v[178:181], v[186:187], off offset:3072
	s_nop 0
	global_load_dwordx4 v[166:169], v[4:5], off offset:2048
	global_load_dwordx4 v[170:173], v[4:5], off offset:3072
	v_add_u32_e32 v3, v224, v222
	s_waitcnt vmcnt(0)
	v_mul_f32_e32 v134, 0xbfb8aa3b, v134
	v_mul_f32_e32 v135, 0xbfb8aa3b, v135
	v_mul_f32_e32 v136, 0xbfb8aa3b, v136
	v_mul_f32_e32 v137, 0xbfb8aa3b, v137
	v_mul_f32_e32 v138, 0xbfb8aa3b, v138
	v_mul_f32_e32 v139, 0xbfb8aa3b, v139
	v_mul_f32_e32 v140, 0xbfb8aa3b, v140
	v_mul_f32_e32 v141, 0xbfb8aa3b, v141
	v_mul_f32_e32 v142, 0xbfb8aa3b, v142
	v_mul_f32_e32 v143, 0xbfb8aa3b, v143
	v_mul_f32_e32 v144, 0xbfb8aa3b, v144
	v_mul_f32_e32 v145, 0xbfb8aa3b, v145
	v_mul_f32_e32 v146, 0xbfb8aa3b, v146
	v_mul_f32_e32 v147, 0xbfb8aa3b, v147
	v_mul_f32_e32 v148, 0xbfb8aa3b, v148
	v_mul_f32_e32 v149, 0xbfb8aa3b, v149
	v_mul_f32_e32 v150, 0xbfb8aa3b, v150
	v_mul_f32_e32 v151, 0xbfb8aa3b, v151
	v_mul_f32_e32 v152, 0xbfb8aa3b, v152
	v_mul_f32_e32 v153, 0xbfb8aa3b, v153
	v_mul_f32_e32 v154, 0xbfb8aa3b, v154
	v_mul_f32_e32 v155, 0xbfb8aa3b, v155
	v_mul_f32_e32 v156, 0xbfb8aa3b, v156
	v_mul_f32_e32 v157, 0xbfb8aa3b, v157
	v_mul_f32_e32 v158, 0xbfb8aa3b, v158
	v_mul_f32_e32 v159, 0xbfb8aa3b, v159
	v_mul_f32_e32 v160, 0xbfb8aa3b, v160
	v_mul_f32_e32 v161, 0xbfb8aa3b, v161
	v_mul_f32_e32 v162, 0xbfb8aa3b, v162
	v_mul_f32_e32 v163, 0xbfb8aa3b, v163
	v_mul_f32_e32 v164, 0xbfb8aa3b, v164
	v_mul_f32_e32 v165, 0xbfb8aa3b, v165
	ds_write_b128 v3, v[190:193]
	ds_write_b128 v3, v[194:197] offset:1152
	ds_read_b128 v[190:193], v188
	ds_read_b128 v[194:197], v188 offset:64
	ds_write_b128 v3, v[228:231]
	ds_write_b128 v3, v[232:235] offset:1152
	ds_read_b128 v[228:231], v188
	ds_read_b128 v[232:235], v188 offset:64
	s_waitcnt lgkmcnt(0)
	v_lshlrev_b32_e32 v189, 16, v190
	v_and_b32_e32 v190, 0xffff0000, v190
	v_lshlrev_b32_e32 v227, 16, v191
	v_and_b32_e32 v237, 0xffff0000, v191
	v_lshlrev_b32_e32 v191, 16, v192
	v_fma_f32 v189, v189, s89, v158
	v_and_b32_e32 v192, 0xffff0000, v192
	v_lshlrev_b32_e32 v239, 16, v193
	v_and_b32_e32 v241, 0xffff0000, v193
	v_lshlrev_b32_e32 v193, 16, v228
	v_and_b32_e32 v228, 0xffff0000, v228
	v_lshlrev_b32_e32 v236, 16, v229
	v_and_b32_e32 v242, 0xffff0000, v229
	v_lshlrev_b32_e32 v229, 16, v230
	v_fma_f32 v191, v191, s89, v150
	v_fma_f32 v190, v190, s89, v159
	v_fma_f32 v192, v192, s89, v151
	v_fma_f32 v193, v193, s89, v162
	v_fma_f32 v229, v229, s89, v154
	v_fma_f32 v228, v228, s89, v163
	v_med3_f32 v189, v189, s85, v226
	v_med3_f32 v191, v191, s85, v226
	v_med3_f32 v190, v190, s85, v226
	v_exp_f32_e32 v189, v189
	v_med3_f32 v238, v192, s85, v226
	v_med3_f32 v192, v193, s85, v226
	v_med3_f32 v193, v229, s85, v226
	v_exp_f32_e32 v229, v191
	v_med3_f32 v191, v228, s85, v226
	v_exp_f32_e32 v228, v190
	v_add_f32_e32 v189, 1.0, v189
	v_exp_f32_e32 v190, v192
	v_exp_f32_e32 v192, v193
	v_add_f32_e32 v193, 1.0, v229
	v_add_f32_e32 v229, 1.0, v228
	v_rcp_f32_e32 v228, v189
	v_exp_f32_e32 v189, v238
	v_fma_f32 v227, v227, s89, v160
	v_and_b32_e32 v230, 0xffff0000, v230
	v_med3_f32 v227, v227, s85, v226
	v_lshlrev_b32_e32 v240, 16, v231
	v_and_b32_e32 v243, 0xffff0000, v231
	v_fma_f32 v231, v230, s89, v155
	v_add_f32_e32 v189, 1.0, v189
	v_exp_f32_e32 v227, v227
	v_rcp_f32_e32 v230, v193
	v_med3_f32 v193, v231, s85, v226
	v_rcp_f32_e32 v231, v189
	v_fma_f32 v189, v236, s89, v164
	v_med3_f32 v189, v189, s85, v226
	v_exp_f32_e32 v236, v189
	v_add_f32_e32 v189, 1.0, v227
	v_fma_f32 v227, v239, s89, v152
	v_med3_f32 v227, v227, s85, v226
	v_exp_f32_e32 v227, v227
	v_rcp_f32_e32 v238, v189
	v_fma_f32 v189, v240, s89, v156
	v_med3_f32 v189, v189, s85, v226
	v_fma_f32 v237, v237, s89, v161
	v_exp_f32_e32 v240, v189
	v_add_f32_e32 v189, 1.0, v227
	v_fma_f32 v227, v242, s89, v165
	v_med3_f32 v237, v237, s85, v226
	v_exp_f32_e32 v239, v237
	v_med3_f32 v227, v227, s85, v226
	v_exp_f32_e32 v237, v227
	v_fma_f32 v227, v241, s89, v153
	v_med3_f32 v227, v227, s85, v226
	v_rcp_f32_e32 v242, v189
	v_add_f32_e32 v189, 1.0, v239
	v_exp_f32_e32 v227, v227
	v_rcp_f32_e32 v239, v189
	v_fma_f32 v189, v243, s89, v157
; #define UNPK0(q_) ((f32x4){bf_lo((q_).x), bf_hi((q_).x), bf_lo((q_).y), bf_hi((q_).y)})
; #define UNPK1(q_) ((f32x4){bf_lo((q_).z), bf_hi((q_).z), bf_lo((q_).w), bf_hi((q_).w)})
;     static __device__ __forceinline__ float eneg(float g) { return __builtin_amdgcn_exp2f(-1.4426950408889634f * fminf(fmaxf(g, -30.f), 30.f)); }
;     __device__ __forceinline__ void mid(f32x4 (&acc)[2][2][4][2], const Unit& u, int wr, int wc, int fr, int fq) const {
;     ...
;                 for (int bj = 0; bj < 2; ++bj) { const u32x4 ga = bj ? ga1 : ga0, gb = bj ? gb1 : gb0;
;                     const f32x4 a0 = UNPK0(ga) + ba[bj][0], a1 = UNPK1(ga) + ba[bj][1], b0 = UNPK0(gb) + bb[bj][0], b1 = UNPK1(gb) + bb[bj][1];
; #pragma unroll
;                     for (int k = 0; k < 4; ++k) { acc[ai][bj][m][0][k] *= (1.0f + eneg(b0[k])) * __builtin_amdgcn_rcpf(1.0f + eneg(a0[k]));
;                                                   acc[ai][bj][m][1][k] *= (1.0f + eneg(b1[k])) * __builtin_amdgcn_rcpf(1.0f + eneg(a1[k])); } } }
	v_exp_f32_e32 v193, v193
	v_med3_f32 v189, v189, s85, v226
	v_exp_f32_e32 v241, v189
	v_add_f32_e32 v189, 1.0, v227
	v_exp_f32_e32 v191, v191
	v_rcp_f32_e32 v243, v189
	v_lshlrev_b32_e32 v189, 16, v194
	v_rcp_f32_e32 v229, v229
	v_fma_f32 v189, v189, s89, v142
	v_pk_add_f32 v[192:193], v[192:193], 1.0 op_sel_hi:[1,0]
	v_pk_mul_f32 v[192:193], v[230:231], v[192:193]
	v_med3_f32 v189, v189, s85, v226
	v_pk_add_f32 v[190:191], v[190:191], 1.0 op_sel_hi:[1,0]
	v_pk_mul_f32 v[126:127], v[126:127], v[192:193]
	v_lshlrev_b32_e32 v193, 16, v196
	v_exp_f32_e32 v189, v189
	v_pk_mul_f32 v[190:191], v[228:229], v[190:191]
	v_fma_f32 v193, v193, s89, v134
	v_pk_mul_f32 v[130:131], v[130:131], v[190:191]
	v_pk_add_f32 v[190:191], v[240:241], 1.0 op_sel_hi:[1,0]
	v_pk_mul_f32 v[190:191], v[242:243], v[190:191]
	v_med3_f32 v193, v193, s85, v226
	v_pk_mul_f32 v[128:129], v[128:129], v[190:191]
	v_and_b32_e32 v191, 0xffff0000, v194
	v_lshlrev_b32_e32 v194, 16, v234
	v_add_f32_e32 v189, 1.0, v189
	v_exp_f32_e32 v193, v193
	v_rcp_f32_e32 v192, v189
	v_fma_f32 v189, v194, s89, v138
	v_fma_f32 v191, v191, s89, v143
	v_pk_add_f32 v[236:237], v[236:237], 1.0 op_sel_hi:[1,0]
	v_pk_mul_f32 v[228:229], v[238:239], v[236:237]
	v_med3_f32 v189, v189, s85, v226
	v_med3_f32 v191, v191, s85, v226
	v_pk_mul_f32 v[132:133], v[132:133], v[228:229]
	v_lshlrev_b32_e32 v227, 16, v195
	v_and_b32_e32 v229, 0xffff0000, v195
	v_and_b32_e32 v195, 0xffff0000, v196
	v_lshlrev_b32_e32 v231, 16, v197
	v_and_b32_e32 v236, 0xffff0000, v197
	v_and_b32_e32 v197, 0xffff0000, v232
	v_exp_f32_e32 v194, v189
	v_add_f32_e32 v189, 1.0, v193
	v_exp_f32_e32 v193, v191
	v_rcp_f32_e32 v196, v189
	v_fma_f32 v189, v197, s89, v147
	v_fma_f32 v195, v195, s89, v135
	v_med3_f32 v189, v189, s85, v226
	v_med3_f32 v195, v195, s85, v226
	v_and_b32_e32 v230, 0xffff0000, v234
	v_exp_f32_e32 v191, v189
	v_add_f32_e32 v189, 1.0, v193
	v_exp_f32_e32 v197, v195
	v_rcp_f32_e32 v193, v189
	v_fma_f32 v189, v230, s89, v139
	v_fma_f32 v227, v227, s89, v144
	v_med3_f32 v189, v189, s85, v226
	v_med3_f32 v227, v227, s85, v226
	v_lshlrev_b32_e32 v228, 16, v233
	v_exp_f32_e32 v195, v189
	v_add_f32_e32 v189, 1.0, v197
	v_exp_f32_e32 v227, v227
	v_rcp_f32_e32 v197, v189
	v_fma_f32 v189, v228, s89, v148
	v_med3_f32 v189, v189, s85, v226
	v_exp_f32_e32 v228, v189
	v_add_f32_e32 v189, 1.0, v227
	v_fma_f32 v227, v231, s89, v136
	v_med3_f32 v227, v227, s85, v226
	v_lshlrev_b32_e32 v190, 16, v232
	v_lshlrev_b32_e32 v232, 16, v235
	v_exp_f32_e32 v227, v227
	v_fma_f32 v229, v229, s89, v145
	v_rcp_f32_e32 v230, v189
	v_fma_f32 v189, v232, s89, v140
	v_med3_f32 v229, v229, s85, v226
	v_and_b32_e32 v233, 0xffff0000, v233
	v_med3_f32 v189, v189, s85, v226
	v_exp_f32_e32 v231, v229
	v_fma_f32 v190, v190, s89, v146
	v_exp_f32_e32 v232, v189
	v_add_f32_e32 v189, 1.0, v227
	v_fma_f32 v227, v233, s89, v149
	v_med3_f32 v190, v190, s85, v226
	v_med3_f32 v227, v227, s85, v226
	v_exp_f32_e32 v190, v190
	v_exp_f32_e32 v229, v227
	v_rcp_f32_e32 v234, v189
	v_add_f32_e32 v189, 1.0, v231
	v_rcp_f32_e32 v231, v189
	v_pk_add_f32 v[228:229], v[228:229], 1.0 op_sel_hi:[1,0]
	v_pk_add_f32 v[190:191], v[190:191], 1.0 op_sel_hi:[1,0]
	v_and_b32_e32 v235, 0xffff0000, v235
	v_pk_mul_f32 v[190:191], v[192:193], v[190:191]
	v_pk_mul_f32 v[192:193], v[230:231], v[228:229]
	v_fma_f32 v189, v235, s89, v141
	v_pk_mul_f32 v[124:125], v[124:125], v[192:193]
	v_fma_f32 v192, v236, s89, v137
	v_med3_f32 v192, v192, s85, v226
	v_exp_f32_e32 v192, v192
	v_med3_f32 v189, v189, s85, v226
	v_exp_f32_e32 v233, v189
	v_add_f32_e32 v189, 1.0, v192
	v_rcp_f32_e32 v235, v189
	ds_write_b128 v3, v[174:177]
	ds_write_b128 v3, v[178:181] offset:1152
	ds_read_b128 v[174:177], v188
	ds_read_b128 v[178:181], v188 offset:64
	ds_write_b128 v3, v[166:169]
	ds_write_b128 v3, v[170:173] offset:1152
	ds_read_b128 v[166:169], v188
	ds_read_b128 v[170:173], v188 offset:64
	v_pk_mul_f32 v[122:123], v[122:123], v[190:191]
	v_pk_add_f32 v[190:191], v[232:233], 1.0 op_sel_hi:[1,0]
	s_waitcnt lgkmcnt(5)
	v_lshlrev_b32_e32 v189, 16, v174
	v_pk_mul_f32 v[190:191], v[234:235], v[190:191]
	s_waitcnt lgkmcnt(1)
	v_lshlrev_b32_e32 v227, 16, v169
	v_pk_mul_f32 v[120:121], v[120:121], v[190:191]
	v_and_b32_e32 v190, 0xffff0000, v174
	v_lshlrev_b32_e32 v174, 16, v176
	v_and_b32_e32 v228, 0xffff0000, v169
	v_fma_f32 v169, v174, s89, v150
	v_pk_add_f32 v[192:193], v[194:195], 1.0 op_sel_hi:[1,0]
	v_pk_mul_f32 v[192:193], v[196:197], v[192:193]
	v_med3_f32 v169, v169, s85, v226
	v_pk_mul_f32 v[118:119], v[118:119], v[192:193]
	v_lshlrev_b32_e32 v191, 16, v175
	v_and_b32_e32 v193, 0xffff0000, v175
	v_and_b32_e32 v175, 0xffff0000, v176
	v_lshlrev_b32_e32 v192, 16, v167
	v_and_b32_e32 v196, 0xffff0000, v167
	v_lshlrev_b32_e32 v167, 16, v168
	v_exp_f32_e32 v169, v169
	v_fma_f32 v167, v167, s89, v154
	v_fma_f32 v175, v175, s89, v151
	v_med3_f32 v167, v167, s85, v226
	v_med3_f32 v175, v175, s85, v226
	v_and_b32_e32 v197, 0xffff0000, v168
	v_fma_f32 v168, v189, s89, v158
	v_exp_f32_e32 v174, v167
	v_add_f32_e32 v167, 1.0, v169
	v_fma_f32 v169, v190, s89, v159
	v_exp_f32_e32 v189, v175
	v_fma_f32 v190, v191, s89, v160
	v_lshlrev_b32_e32 v194, 16, v177
	v_and_b32_e32 v195, 0xffff0000, v177
	v_lshlrev_b32_e32 v176, 16, v166
	v_and_b32_e32 v177, 0xffff0000, v166
	v_med3_f32 v190, v190, s85, v226
	v_fma_f32 v166, v176, s89, v162
	v_rcp_f32_e32 v176, v167
	v_fma_f32 v167, v177, s89, v163
	v_fma_f32 v177, v197, s89, v155
	v_exp_f32_e32 v191, v190
	v_med3_f32 v175, v177, s85, v226
	v_add_f32_e32 v177, 1.0, v189
	v_fma_f32 v189, v192, s89, v164
	v_med3_f32 v189, v189, s85, v226
	v_exp_f32_e32 v190, v189
	v_add_f32_e32 v189, 1.0, v191
; #define UNPK0(q_) ((f32x4){bf_lo((q_).x), bf_hi((q_).x), bf_lo((q_).y), bf_hi((q_).y)})
; #define UNPK1(q_) ((f32x4){bf_lo((q_).z), bf_hi((q_).z), bf_lo((q_).w), bf_hi((q_).w)})
;     static __device__ __forceinline__ float eneg(float g) { return __builtin_amdgcn_exp2f(-1.4426950408889634f * fminf(fmaxf(g, -30.f), 30.f)); }
;     __device__ __forceinline__ void mid(f32x4 (&acc)[2][2][4][2], const Unit& u, int wr, int wc, int fr, int fq) const {
;     ...
;         for (int am = 0; am < 4; ++am) { const int ai = am >> 1;
;             u32x4 ra[4][2], rb[4][2];
; #pragma unroll
;             for (int m = 2 * (am & 1); m < 2 * (am & 1) + 2; ++m) { pa.fetch(ai, m, ra[m][0], ra[m][1]); pb.fetch(ai, m, rb[m][0], rb[m][1]); }
;             asm volatile("" ::: "memory");
; #pragma unroll
;             for (int m = 2 * (am & 1); m < 2 * (am & 1) + 2; ++m) {
;                 pa.stage(ra[m][0], ra[m][1]); const u32x4 ga0 = pa.get(0), ga1 = pa.get(1);
;                 asm volatile("" ::: "memory");
;                 pb.stage(rb[m][0], rb[m][1]); const u32x4 gb0 = pb.get(0), gb1 = pb.get(1);
;                 asm volatile("" ::: "memory");
; #pragma unroll
;                 for (int bj = 0; bj < 2; ++bj) { const u32x4 ga = bj ? ga1 : ga0, gb = bj ? gb1 : gb0;
;                     const f32x4 a0 = UNPK0(ga) + ba[bj][0], a1 = UNPK1(ga) + ba[bj][1], b0 = UNPK0(gb) + bb[bj][0], b1 = UNPK1(gb) + bb[bj][1];
; #pragma unroll
;                     for (int k = 0; k < 4; ++k) { acc[ai][bj][m][0][k] *= (1.0f + eneg(b0[k])) * __builtin_amdgcn_rcpf(1.0f + eneg(a0[k]));
;                                                   acc[ai][bj][m][1][k] *= (1.0f + eneg(b1[k])) * __builtin_amdgcn_rcpf(1.0f + eneg(a1[k])); } } }
	v_fma_f32 v191, v194, s89, v152
	v_med3_f32 v191, v191, s85, v226
	v_exp_f32_e32 v191, v191
	v_fma_f32 v193, v193, s89, v161
	v_rcp_f32_e32 v192, v189
	v_fma_f32 v189, v227, s89, v156
	v_med3_f32 v168, v168, s85, v226
	v_med3_f32 v169, v169, s85, v226
	v_med3_f32 v193, v193, s85, v226
	v_exp_f32_e32 v168, v168
	v_exp_f32_e32 v169, v169
	v_med3_f32 v189, v189, s85, v226
	v_exp_f32_e32 v193, v193
	v_exp_f32_e32 v194, v189
	v_add_f32_e32 v189, 1.0, v191
	v_fma_f32 v191, v196, s89, v165
	v_med3_f32 v166, v166, s85, v226
	v_med3_f32 v167, v167, s85, v226
	v_med3_f32 v191, v191, s85, v226
	v_exp_f32_e32 v166, v166
	v_add_f32_e32 v168, 1.0, v168
	v_exp_f32_e32 v167, v167
	v_add_f32_e32 v169, 1.0, v169
	v_exp_f32_e32 v191, v191
	v_rcp_f32_e32 v196, v189
	v_add_f32_e32 v189, 1.0, v193
	v_rcp_f32_e32 v168, v168
	v_rcp_f32_e32 v169, v169
	v_rcp_f32_e32 v193, v189
	v_pk_add_f32 v[190:191], v[190:191], 1.0 op_sel_hi:[1,0]
	v_pk_add_f32 v[166:167], v[166:167], 1.0 op_sel_hi:[1,0]
	v_pk_mul_f32 v[166:167], v[168:169], v[166:167]
	v_pk_mul_f32 v[168:169], v[192:193], v[190:191]
	v_exp_f32_e32 v175, v175
	v_pk_mul_f32 v[116:117], v[116:117], v[168:169]
	v_fma_f32 v169, v195, s89, v153
	v_med3_f32 v169, v169, s85, v226
	v_exp_f32_e32 v169, v169
	v_fma_f32 v168, v228, s89, v157
	v_med3_f32 v168, v168, s85, v226
	v_rcp_f32_e32 v177, v177
	v_exp_f32_e32 v195, v168
	v_pk_mul_f32 v[114:115], v[114:115], v[166:167]
	v_add_f32_e32 v166, 1.0, v169
	v_rcp_f32_e32 v197, v166
	v_pk_add_f32 v[168:169], v[174:175], 1.0 op_sel_hi:[1,0]
	v_pk_add_f32 v[166:167], v[194:195], 1.0 op_sel_hi:[1,0]
	v_pk_mul_f32 v[168:169], v[176:177], v[168:169]
	v_pk_mul_f32 v[166:167], v[196:197], v[166:167]
	v_pk_mul_f32 v[110:111], v[110:111], v[168:169]
	v_lshlrev_b32_e32 v169, 16, v180
	v_pk_mul_f32 v[112:113], v[112:113], v[166:167]
	v_lshlrev_b32_e32 v166, 16, v178
	v_fma_f32 v169, v169, s89, v134
	v_fma_f32 v166, v166, s89, v142
	v_med3_f32 v169, v169, s85, v226
	v_med3_f32 v166, v166, s85, v226
	v_exp_f32_e32 v169, v169
	v_and_b32_e32 v167, 0xffff0000, v178
	v_and_b32_e32 v176, 0xffff0000, v180
	s_waitcnt lgkmcnt(0)
	v_lshlrev_b32_e32 v168, 16, v170
	v_and_b32_e32 v178, 0xffff0000, v170
	v_lshlrev_b32_e32 v180, 16, v171
	v_and_b32_e32 v189, 0xffff0000, v171
	v_lshlrev_b32_e32 v170, 16, v172
	v_and_b32_e32 v171, 0xffff0000, v172
	v_exp_f32_e32 v172, v166
	v_fma_f32 v168, v168, s89, v146
	v_add_f32_e32 v169, 1.0, v169
	v_med3_f32 v166, v168, s85, v226
	v_add_f32_e32 v168, 1.0, v172
	v_rcp_f32_e32 v172, v169
	v_fma_f32 v169, v178, s89, v147
	v_add_co_u32_e32 v178, vcc, s84, v186
	v_lshlrev_b32_e32 v174, 16, v179
	v_and_b32_e32 v175, 0xffff0000, v179
	v_addc_co_u32_e32 v179, vcc, 0, v187, vcc
	global_load_dwordx4 v[190:193], v[178:179], off
	global_load_dwordx4 v[194:197], v[178:179], off offset:1024
	v_add_co_u32_e32 v236, vcc, s84, v4
	v_fma_f32 v167, v167, s89, v143
	s_nop 0
	v_addc_co_u32_e32 v237, vcc, 0, v5, vcc
	global_load_dwordx4 v[228:231], v[236:237], off
	global_load_dwordx4 v[232:235], v[236:237], off offset:1024
	v_med3_f32 v167, v167, s85, v226
	v_lshlrev_b32_e32 v227, 16, v173
	v_and_b32_e32 v239, 0xffff0000, v173
	v_exp_f32_e32 v173, v167
	v_fma_f32 v174, v174, s89, v144
	v_lshlrev_b32_e32 v177, 16, v181
	v_med3_f32 v174, v174, s85, v226
	v_med3_f32 v167, v169, s85, v226
	v_add_f32_e32 v169, 1.0, v173
	v_fma_f32 v173, v176, s89, v135
	v_fma_f32 v176, v180, s89, v148
	v_exp_f32_e32 v180, v174
	v_fma_f32 v177, v177, s89, v136
	v_fma_f32 v175, v175, s89, v145
	v_med3_f32 v177, v177, s85, v226
	v_exp_f32_e32 v177, v177
	v_med3_f32 v175, v175, s85, v226
	v_med3_f32 v174, v176, s85, v226
	v_add_f32_e32 v176, 1.0, v180
	v_fma_f32 v180, v227, s89, v140
	v_exp_f32_e32 v227, v175
	v_fma_f32 v189, v189, s89, v149
	v_add_f32_e32 v177, 1.0, v177
	v_med3_f32 v175, v189, s85, v226
	v_exp_f32_e32 v166, v166
	v_exp_f32_e32 v167, v167
	v_exp_f32_e32 v174, v174
	v_exp_f32_e32 v175, v175
	v_rcp_f32_e32 v238, v177
	v_add_f32_e32 v177, 1.0, v227
	v_rcp_f32_e32 v168, v168
	v_rcp_f32_e32 v169, v169
	v_rcp_f32_e32 v176, v176
	v_rcp_f32_e32 v177, v177
	v_pk_add_f32 v[174:175], v[174:175], 1.0 op_sel_hi:[1,0]
	v_pk_add_f32 v[166:167], v[166:167], 1.0 op_sel_hi:[1,0]
	v_and_b32_e32 v181, 0xffff0000, v181
	v_pk_mul_f32 v[166:167], v[168:169], v[166:167]
	v_pk_mul_f32 v[168:169], v[176:177], v[174:175]
	v_pk_mul_f32 v[108:109], v[108:109], v[168:169]
	v_fma_f32 v169, v181, s89, v137
	v_med3_f32 v173, v173, s85, v226
	v_med3_f32 v169, v169, s85, v226
	v_exp_f32_e32 v173, v173
	v_exp_f32_e32 v169, v169
	v_fma_f32 v170, v170, s89, v138
	v_fma_f32 v171, v171, s89, v139
	v_fma_f32 v168, v239, s89, v141
	v_med3_f32 v170, v170, s85, v226
	v_med3_f32 v171, v171, s85, v226
	v_med3_f32 v180, v180, s85, v226
	v_med3_f32 v168, v168, s85, v226
	v_exp_f32_e32 v170, v170
	v_exp_f32_e32 v171, v171
	v_add_f32_e32 v173, 1.0, v173
	v_exp_f32_e32 v180, v180
	v_exp_f32_e32 v181, v168
	v_pk_mul_f32 v[106:107], v[106:107], v[166:167]
	v_add_f32_e32 v166, 1.0, v169
	v_rcp_f32_e32 v173, v173
	v_rcp_f32_e32 v239, v166
	v_pk_add_f32 v[166:167], v[180:181], 1.0 op_sel_hi:[1,0]
	v_pk_add_f32 v[168:169], v[170:171], 1.0 op_sel_hi:[1,0]
	v_pk_mul_f32 v[166:167], v[238:239], v[166:167]
	v_pk_mul_f32 v[168:169], v[172:173], v[168:169]
	v_pk_mul_f32 v[104:105], v[104:105], v[166:167]
	v_pk_mul_f32 v[102:103], v[102:103], v[168:169]
	global_load_dwordx4 v[174:177], v[178:179], off offset:2048
	s_nop 0
	global_load_dwordx4 v[178:181], v[178:179], off offset:3072
	s_nop 0
	global_load_dwordx4 v[166:169], v[236:237], off offset:2048
	global_load_dwordx4 v[170:173], v[236:237], off offset:3072
	s_waitcnt vmcnt(7)
; #define UNPK0(q_) ((f32x4){bf_lo((q_).x), bf_hi((q_).x), bf_lo((q_).y), bf_hi((q_).y)})
; #define UNPK1(q_) ((f32x4){bf_lo((q_).z), bf_hi((q_).z), bf_lo((q_).w), bf_hi((q_).w)})
;     static __device__ __forceinline__ float eneg(float g) { return __builtin_amdgcn_exp2f(-1.4426950408889634f * fminf(fmaxf(g, -30.f), 30.f)); }
;     __device__ __forceinline__ void mid(f32x4 (&acc)[2][2][4][2], const Unit& u, int wr, int wc, int fr, int fq) const {
;     ...
;             for (int m = 2 * (am & 1); m < 2 * (am & 1) + 2; ++m) {
;                 pa.stage(ra[m][0], ra[m][1]); const u32x4 ga0 = pa.get(0), ga1 = pa.get(1);
;                 asm volatile("" ::: "memory");
;                 pb.stage(rb[m][0], rb[m][1]); const u32x4 gb0 = pb.get(0), gb1 = pb.get(1);
;                 asm volatile("" ::: "memory");
; #pragma unroll
;                 for (int bj = 0; bj < 2; ++bj) { const u32x4 ga = bj ? ga1 : ga0, gb = bj ? gb1 : gb0;
;                     const f32x4 a0 = UNPK0(ga) + ba[bj][0], a1 = UNPK1(ga) + ba[bj][1], b0 = UNPK0(gb) + bb[bj][0], b1 = UNPK1(gb) + bb[bj][1];
; #pragma unroll
;                     for (int k = 0; k < 4; ++k) { acc[ai][bj][m][0][k] *= (1.0f + eneg(b0[k])) * __builtin_amdgcn_rcpf(1.0f + eneg(a0[k]));
;                                                   acc[ai][bj][m][1][k] *= (1.0f + eneg(b1[k])) * __builtin_amdgcn_rcpf(1.0f + eneg(a1[k])); } } }
	ds_write_b128 v3, v[190:193]
	s_waitcnt vmcnt(6)
	ds_write_b128 v3, v[194:197] offset:1152
	ds_read_b128 v[190:193], v188
	ds_read_b128 v[194:197], v188 offset:64
	s_waitcnt vmcnt(5)
	ds_write_b128 v3, v[228:231]
	s_waitcnt vmcnt(4)
	ds_write_b128 v3, v[232:235] offset:1152
	ds_read_b128 v[228:231], v188
	ds_read_b128 v[232:235], v188 offset:64
	s_waitcnt lgkmcnt(5)
	v_lshlrev_b32_e32 v189, 16, v190
	v_fma_f32 v189, v189, s89, v158
	v_med3_f32 v189, v189, s85, v226
	v_lshlrev_b32_e32 v236, 16, v191
	v_and_b32_e32 v237, 0xffff0000, v191
	v_lshlrev_b32_e32 v191, 16, v192
	v_exp_f32_e32 v189, v189
	v_fma_f32 v191, v191, s89, v150
	v_med3_f32 v191, v191, s85, v226
	v_and_b32_e32 v227, 0xffff0000, v190
	v_lshlrev_b32_e32 v239, 16, v193
	v_and_b32_e32 v241, 0xffff0000, v193
	s_waitcnt lgkmcnt(1)
	v_lshlrev_b32_e32 v190, 16, v228
	v_and_b32_e32 v193, 0xffff0000, v228
	v_lshlrev_b32_e32 v228, 16, v230
	v_add_f32_e32 v189, 1.0, v189
	v_exp_f32_e32 v191, v191
	v_and_b32_e32 v238, 0xffff0000, v192
	v_rcp_f32_e32 v192, v189
	v_fma_f32 v189, v228, s89, v154
	v_med3_f32 v189, v189, s85, v226
	v_exp_f32_e32 v228, v189
	v_add_f32_e32 v189, 1.0, v191
	v_fma_f32 v191, v227, s89, v159
	v_med3_f32 v191, v191, s85, v226
	v_lshlrev_b32_e32 v240, 16, v229
	v_and_b32_e32 v242, 0xffff0000, v229
	v_and_b32_e32 v229, 0xffff0000, v230
	v_rcp_f32_e32 v230, v189
	v_fma_f32 v189, v193, s89, v163
	v_exp_f32_e32 v193, v191
	v_fma_f32 v227, v238, s89, v151
	v_med3_f32 v189, v189, s85, v226
	v_med3_f32 v227, v227, s85, v226
	v_exp_f32_e32 v191, v189
	v_add_f32_e32 v189, 1.0, v193
	v_exp_f32_e32 v227, v227
	v_rcp_f32_e32 v193, v189
	v_fma_f32 v189, v229, s89, v155
	v_med3_f32 v189, v189, s85, v226
	v_exp_f32_e32 v229, v189
	v_add_f32_e32 v189, 1.0, v227
	v_fma_f32 v227, v236, s89, v160
	v_med3_f32 v227, v227, s85, v226
	v_exp_f32_e32 v227, v227
	v_lshlrev_b32_e32 v243, 16, v231
	v_and_b32_e32 v244, 0xffff0000, v231
	v_rcp_f32_e32 v231, v189
	v_fma_f32 v189, v240, s89, v164
	v_med3_f32 v189, v189, s85, v226
	v_exp_f32_e32 v236, v189
	v_add_f32_e32 v189, 1.0, v227
	v_fma_f32 v227, v239, s89, v152
	v_med3_f32 v227, v227, s85, v226
	v_exp_f32_e32 v227, v227
	v_fma_f32 v237, v237, s89, v161
	v_rcp_f32_e32 v238, v189
	v_fma_f32 v189, v243, s89, v156
	v_med3_f32 v237, v237, s85, v226
	v_med3_f32 v189, v189, s85, v226
	v_exp_f32_e32 v239, v237
	v_fma_f32 v190, v190, s89, v162
	v_exp_f32_e32 v240, v189
	v_add_f32_e32 v189, 1.0, v227
	v_fma_f32 v227, v242, s89, v165
	v_med3_f32 v190, v190, s85, v226
	v_med3_f32 v227, v227, s85, v226
	v_exp_f32_e32 v190, v190
	v_exp_f32_e32 v237, v227
	v_rcp_f32_e32 v242, v189
	v_add_f32_e32 v189, 1.0, v239
	v_rcp_f32_e32 v239, v189
	v_pk_add_f32 v[236:237], v[236:237], 1.0 op_sel_hi:[1,0]
	v_pk_add_f32 v[190:191], v[190:191], 1.0 op_sel_hi:[1,0]
	v_fma_f32 v189, v244, s89, v157
	v_pk_mul_f32 v[190:191], v[192:193], v[190:191]
	v_pk_mul_f32 v[192:193], v[238:239], v[236:237]
	v_pk_mul_f32 v[100:101], v[100:101], v[192:193]
	v_fma_f32 v192, v241, s89, v153
	v_med3_f32 v192, v192, s85, v226
	v_exp_f32_e32 v192, v192
	v_med3_f32 v189, v189, s85, v226
	v_exp_f32_e32 v241, v189
	v_pk_mul_f32 v[98:99], v[98:99], v[190:191]
	v_add_f32_e32 v189, 1.0, v192
	v_rcp_f32_e32 v243, v189
	v_lshlrev_b32_e32 v189, 16, v194
	v_fma_f32 v189, v189, s89, v142
	v_pk_add_f32 v[192:193], v[228:229], 1.0 op_sel_hi:[1,0]
	v_pk_mul_f32 v[192:193], v[230:231], v[192:193]
	v_med3_f32 v189, v189, s85, v226
	v_pk_mul_f32 v[94:95], v[94:95], v[192:193]
	v_lshlrev_b32_e32 v193, 16, v196
	v_exp_f32_e32 v189, v189
	v_fma_f32 v193, v193, s89, v134
	v_pk_add_f32 v[190:191], v[240:241], 1.0 op_sel_hi:[1,0]
	v_pk_mul_f32 v[190:191], v[242:243], v[190:191]
	v_med3_f32 v193, v193, s85, v226
	v_pk_mul_f32 v[96:97], v[96:97], v[190:191]
	v_and_b32_e32 v191, 0xffff0000, v194
	s_waitcnt lgkmcnt(0)
	v_lshlrev_b32_e32 v194, 16, v234
	v_add_f32_e32 v189, 1.0, v189
	v_exp_f32_e32 v193, v193
	v_rcp_f32_e32 v192, v189
	v_fma_f32 v189, v194, s89, v138
	v_fma_f32 v191, v191, s89, v143
	v_med3_f32 v189, v189, s85, v226
	v_med3_f32 v191, v191, s85, v226
	v_lshlrev_b32_e32 v227, 16, v195
	v_and_b32_e32 v229, 0xffff0000, v195
	v_and_b32_e32 v195, 0xffff0000, v196
	v_lshlrev_b32_e32 v231, 16, v197
	v_and_b32_e32 v236, 0xffff0000, v197
	v_and_b32_e32 v197, 0xffff0000, v232
	v_exp_f32_e32 v194, v189
	v_add_f32_e32 v189, 1.0, v193
	v_exp_f32_e32 v193, v191
	v_rcp_f32_e32 v196, v189
	v_fma_f32 v189, v197, s89, v147
	v_fma_f32 v195, v195, s89, v135
	v_med3_f32 v189, v189, s85, v226
	v_med3_f32 v195, v195, s85, v226
	v_and_b32_e32 v230, 0xffff0000, v234
	v_exp_f32_e32 v191, v189
	v_add_f32_e32 v189, 1.0, v193
	v_exp_f32_e32 v197, v195
	v_rcp_f32_e32 v193, v189
	v_fma_f32 v189, v230, s89, v139
	v_fma_f32 v227, v227, s89, v144
	v_med3_f32 v189, v189, s85, v226
	v_med3_f32 v227, v227, s85, v226
	v_lshlrev_b32_e32 v228, 16, v233
	v_exp_f32_e32 v195, v189
	v_add_f32_e32 v189, 1.0, v197
	v_exp_f32_e32 v227, v227
	v_rcp_f32_e32 v197, v189
	v_fma_f32 v189, v228, s89, v148
	v_med3_f32 v189, v189, s85, v226
	v_exp_f32_e32 v228, v189
	v_add_f32_e32 v189, 1.0, v227
	v_fma_f32 v227, v231, s89, v136
	v_med3_f32 v227, v227, s85, v226
	v_lshlrev_b32_e32 v190, 16, v232
	v_lshlrev_b32_e32 v232, 16, v235
	v_exp_f32_e32 v227, v227
	v_fma_f32 v229, v229, s89, v145
	v_rcp_f32_e32 v230, v189
	v_fma_f32 v189, v232, s89, v140
	v_med3_f32 v229, v229, s85, v226
	v_and_b32_e32 v233, 0xffff0000, v233
	v_med3_f32 v189, v189, s85, v226
	v_exp_f32_e32 v231, v229
	v_fma_f32 v190, v190, s89, v146
	v_exp_f32_e32 v232, v189
	v_add_f32_e32 v189, 1.0, v227
	v_fma_f32 v227, v233, s89, v149
	v_med3_f32 v190, v190, s85, v226
	v_med3_f32 v227, v227, s85, v226
	v_exp_f32_e32 v190, v190
	v_exp_f32_e32 v229, v227
	v_rcp_f32_e32 v234, v189
	v_add_f32_e32 v189, 1.0, v231
	v_rcp_f32_e32 v231, v189
	v_pk_add_f32 v[228:229], v[228:229], 1.0 op_sel_hi:[1,0]
	v_pk_add_f32 v[190:191], v[190:191], 1.0 op_sel_hi:[1,0]
	v_and_b32_e32 v235, 0xffff0000, v235
	v_pk_mul_f32 v[190:191], v[192:193], v[190:191]
	v_pk_mul_f32 v[192:193], v[230:231], v[228:229]
	v_fma_f32 v189, v235, s89, v141
	v_pk_mul_f32 v[92:93], v[92:93], v[192:193]
	v_fma_f32 v192, v236, s89, v137
	v_med3_f32 v192, v192, s85, v226
	v_exp_f32_e32 v192, v192
	v_med3_f32 v189, v189, s85, v226
	v_exp_f32_e32 v233, v189
	v_add_f32_e32 v189, 1.0, v192
	v_rcp_f32_e32 v235, v189
	s_waitcnt vmcnt(3)
; #define UNPK0(q_) ((f32x4){bf_lo((q_).x), bf_hi((q_).x), bf_lo((q_).y), bf_hi((q_).y)})
; #define UNPK1(q_) ((f32x4){bf_lo((q_).z), bf_hi((q_).z), bf_lo((q_).w), bf_hi((q_).w)})
;     static __device__ __forceinline__ float eneg(float g) { return __builtin_amdgcn_exp2f(-1.4426950408889634f * fminf(fmaxf(g, -30.f), 30.f)); }
;     __device__ __forceinline__ void mid(f32x4 (&acc)[2][2][4][2], const Unit& u, int wr, int wc, int fr, int fq) const {
;     ...
;         for (int am = 0; am < 4; ++am) { const int ai = am >> 1;
;             u32x4 ra[4][2], rb[4][2];
; #pragma unroll
;             for (int m = 2 * (am & 1); m < 2 * (am & 1) + 2; ++m) { pa.fetch(ai, m, ra[m][0], ra[m][1]); pb.fetch(ai, m, rb[m][0], rb[m][1]); }
;             asm volatile("" ::: "memory");
; #pragma unroll
;             for (int m = 2 * (am & 1); m < 2 * (am & 1) + 2; ++m) {
;                 pa.stage(ra[m][0], ra[m][1]); const u32x4 ga0 = pa.get(0), ga1 = pa.get(1);
;                 asm volatile("" ::: "memory");
;                 pb.stage(rb[m][0], rb[m][1]); const u32x4 gb0 = pb.get(0), gb1 = pb.get(1);
;                 asm volatile("" ::: "memory");
; #pragma unroll
;                 for (int bj = 0; bj < 2; ++bj) { const u32x4 ga = bj ? ga1 : ga0, gb = bj ? gb1 : gb0;
;                     const f32x4 a0 = UNPK0(ga) + ba[bj][0], a1 = UNPK1(ga) + ba[bj][1], b0 = UNPK0(gb) + bb[bj][0], b1 = UNPK1(gb) + bb[bj][1];
; #pragma unroll
;                     for (int k = 0; k < 4; ++k) { acc[ai][bj][m][0][k] *= (1.0f + eneg(b0[k])) * __builtin_amdgcn_rcpf(1.0f + eneg(a0[k]));
;                                                   acc[ai][bj][m][1][k] *= (1.0f + eneg(b1[k])) * __builtin_amdgcn_rcpf(1.0f + eneg(a1[k])); } } }
	ds_write_b128 v3, v[174:177]
	s_waitcnt vmcnt(2)
	ds_write_b128 v3, v[178:181] offset:1152
	ds_read_b128 v[174:177], v188
	ds_read_b128 v[178:181], v188 offset:64
	s_waitcnt vmcnt(1)
	ds_write_b128 v3, v[166:169]
	s_waitcnt vmcnt(0)
	ds_write_b128 v3, v[170:173] offset:1152
	ds_read_b128 v[166:169], v188
	ds_read_b128 v[170:173], v188 offset:64
	v_pk_mul_f32 v[90:91], v[90:91], v[190:191]
	v_pk_add_f32 v[190:191], v[232:233], 1.0 op_sel_hi:[1,0]
	s_waitcnt lgkmcnt(5)
	v_lshlrev_b32_e32 v189, 16, v174
	v_pk_mul_f32 v[190:191], v[234:235], v[190:191]
	s_waitcnt lgkmcnt(1)
	v_lshlrev_b32_e32 v227, 16, v169
	v_pk_mul_f32 v[88:89], v[88:89], v[190:191]
	v_and_b32_e32 v190, 0xffff0000, v174
	v_lshlrev_b32_e32 v174, 16, v176
	v_and_b32_e32 v228, 0xffff0000, v169
	v_fma_f32 v169, v174, s89, v150
	v_pk_add_f32 v[192:193], v[194:195], 1.0 op_sel_hi:[1,0]
	v_pk_mul_f32 v[192:193], v[196:197], v[192:193]
	v_med3_f32 v169, v169, s85, v226
	v_pk_mul_f32 v[86:87], v[86:87], v[192:193]
	v_lshlrev_b32_e32 v191, 16, v175
	v_and_b32_e32 v193, 0xffff0000, v175
	v_and_b32_e32 v175, 0xffff0000, v176
	v_lshlrev_b32_e32 v192, 16, v167
	v_and_b32_e32 v196, 0xffff0000, v167
	v_lshlrev_b32_e32 v167, 16, v168
	v_exp_f32_e32 v169, v169
	v_fma_f32 v167, v167, s89, v154
	v_fma_f32 v175, v175, s89, v151
	v_med3_f32 v167, v167, s85, v226
	v_med3_f32 v175, v175, s85, v226
	v_and_b32_e32 v197, 0xffff0000, v168
	v_fma_f32 v168, v189, s89, v158
	v_exp_f32_e32 v174, v167
	v_add_f32_e32 v167, 1.0, v169
	v_fma_f32 v169, v190, s89, v159
	v_exp_f32_e32 v189, v175
	v_fma_f32 v190, v191, s89, v160
	v_lshlrev_b32_e32 v194, 16, v177
	v_and_b32_e32 v195, 0xffff0000, v177
	v_lshlrev_b32_e32 v176, 16, v166
	v_and_b32_e32 v177, 0xffff0000, v166
	v_med3_f32 v190, v190, s85, v226
	v_fma_f32 v166, v176, s89, v162
	v_rcp_f32_e32 v176, v167
	v_fma_f32 v167, v177, s89, v163
	v_fma_f32 v177, v197, s89, v155
	v_exp_f32_e32 v191, v190
	v_med3_f32 v175, v177, s85, v226
	v_add_f32_e32 v177, 1.0, v189
	v_fma_f32 v189, v192, s89, v164
	v_med3_f32 v189, v189, s85, v226
	v_exp_f32_e32 v190, v189
	v_add_f32_e32 v189, 1.0, v191
	v_fma_f32 v191, v194, s89, v152
	v_med3_f32 v191, v191, s85, v226
	v_exp_f32_e32 v191, v191
	v_fma_f32 v193, v193, s89, v161
	v_rcp_f32_e32 v192, v189
	v_fma_f32 v189, v227, s89, v156
	v_med3_f32 v168, v168, s85, v226
	v_med3_f32 v169, v169, s85, v226
	v_med3_f32 v193, v193, s85, v226
	v_exp_f32_e32 v168, v168
	v_exp_f32_e32 v169, v169
	v_med3_f32 v189, v189, s85, v226
	v_exp_f32_e32 v193, v193
	v_exp_f32_e32 v194, v189
	v_add_f32_e32 v189, 1.0, v191
	v_fma_f32 v191, v196, s89, v165
	v_med3_f32 v166, v166, s85, v226
	v_med3_f32 v167, v167, s85, v226
	v_med3_f32 v191, v191, s85, v226
	v_exp_f32_e32 v166, v166
	v_add_f32_e32 v168, 1.0, v168
	v_exp_f32_e32 v167, v167
	v_add_f32_e32 v169, 1.0, v169
	v_exp_f32_e32 v191, v191
	v_rcp_f32_e32 v196, v189
	v_add_f32_e32 v189, 1.0, v193
	v_rcp_f32_e32 v168, v168
	v_rcp_f32_e32 v169, v169
	v_rcp_f32_e32 v193, v189
	v_pk_add_f32 v[190:191], v[190:191], 1.0 op_sel_hi:[1,0]
	v_pk_add_f32 v[166:167], v[166:167], 1.0 op_sel_hi:[1,0]
	v_pk_mul_f32 v[166:167], v[168:169], v[166:167]
	v_pk_mul_f32 v[168:169], v[192:193], v[190:191]
	v_exp_f32_e32 v175, v175
	v_pk_mul_f32 v[84:85], v[84:85], v[168:169]
	v_fma_f32 v169, v195, s89, v153
	v_med3_f32 v169, v169, s85, v226
	v_exp_f32_e32 v169, v169
	v_fma_f32 v168, v228, s89, v157
	v_med3_f32 v168, v168, s85, v226
	v_rcp_f32_e32 v177, v177
	v_exp_f32_e32 v195, v168
	v_pk_mul_f32 v[82:83], v[82:83], v[166:167]
	v_add_f32_e32 v166, 1.0, v169
	v_rcp_f32_e32 v197, v166
	v_pk_add_f32 v[168:169], v[174:175], 1.0 op_sel_hi:[1,0]
	v_pk_add_f32 v[166:167], v[194:195], 1.0 op_sel_hi:[1,0]
	v_pk_mul_f32 v[168:169], v[176:177], v[168:169]
	v_pk_mul_f32 v[166:167], v[196:197], v[166:167]
	v_pk_mul_f32 v[78:79], v[78:79], v[168:169]
	v_lshlrev_b32_e32 v169, 16, v180
	v_pk_mul_f32 v[80:81], v[80:81], v[166:167]
	v_lshlrev_b32_e32 v166, 16, v178
	v_fma_f32 v169, v169, s89, v134
	v_fma_f32 v166, v166, s89, v142
	v_med3_f32 v169, v169, s85, v226
	v_med3_f32 v166, v166, s85, v226
	v_exp_f32_e32 v169, v169
	v_and_b32_e32 v167, 0xffff0000, v178
	v_and_b32_e32 v176, 0xffff0000, v180
	s_waitcnt lgkmcnt(0)
	v_lshlrev_b32_e32 v168, 16, v170
	v_and_b32_e32 v178, 0xffff0000, v170
	v_lshlrev_b32_e32 v180, 16, v171
	v_and_b32_e32 v189, 0xffff0000, v171
	v_lshlrev_b32_e32 v170, 16, v172
	v_and_b32_e32 v171, 0xffff0000, v172
	v_exp_f32_e32 v172, v166
	v_fma_f32 v168, v168, s89, v146
	v_add_f32_e32 v169, 1.0, v169
	v_med3_f32 v166, v168, s85, v226
	v_add_f32_e32 v168, 1.0, v172
	v_rcp_f32_e32 v172, v169
	v_fma_f32 v169, v178, s89, v147
	v_add_co_u32_e32 v178, vcc, s79, v186
	v_lshlrev_b32_e32 v174, 16, v179
	v_and_b32_e32 v175, 0xffff0000, v179
	v_addc_co_u32_e32 v179, vcc, 0, v187, vcc
	v_add_co_u32_e32 v186, vcc, s86, v186
	v_fma_f32 v167, v167, s89, v143
	s_nop 0
	v_addc_co_u32_e32 v187, vcc, 0, v187, vcc
	global_load_dwordx4 v[190:193], v[186:187], off offset:-4096
	global_load_dwordx4 v[194:197], v[178:179], off offset:1024
	v_add_co_u32_e32 v236, vcc, s79, v4
	s_nop 0
	s_nop 0
	v_addc_co_u32_e32 v237, vcc, 0, v5, vcc
	v_add_co_u32_e32 v4, vcc, s86, v4
	v_med3_f32 v167, v167, s85, v226
	s_nop 0
	v_addc_co_u32_e32 v5, vcc, 0, v5, vcc
	global_load_dwordx4 v[228:231], v[4:5], off offset:-4096
	global_load_dwordx4 v[232:235], v[236:237], off offset:1024
	v_lshlrev_b32_e32 v227, 16, v173
	v_and_b32_e32 v239, 0xffff0000, v173
	v_exp_f32_e32 v173, v167
	v_fma_f32 v174, v174, s89, v144
	v_lshlrev_b32_e32 v177, 16, v181
	v_med3_f32 v174, v174, s85, v226
	v_med3_f32 v167, v169, s85, v226
	v_add_f32_e32 v169, 1.0, v173
	v_fma_f32 v173, v176, s89, v135
; #define UNPK0(q_) ((f32x4){bf_lo((q_).x), bf_hi((q_).x), bf_lo((q_).y), bf_hi((q_).y)})
; #define UNPK1(q_) ((f32x4){bf_lo((q_).z), bf_hi((q_).z), bf_lo((q_).w), bf_hi((q_).w)})
;     static __device__ __forceinline__ float eneg(float g) { return __builtin_amdgcn_exp2f(-1.4426950408889634f * fminf(fmaxf(g, -30.f), 30.f)); }
;     __device__ __forceinline__ void mid(f32x4 (&acc)[2][2][4][2], const Unit& u, int wr, int wc, int fr, int fq) const {
;     ...
;             for (int m = 2 * (am & 1); m < 2 * (am & 1) + 2; ++m) {
;                 pa.stage(ra[m][0], ra[m][1]); const u32x4 ga0 = pa.get(0), ga1 = pa.get(1);
;                 asm volatile("" ::: "memory");
;                 pb.stage(rb[m][0], rb[m][1]); const u32x4 gb0 = pb.get(0), gb1 = pb.get(1);
;                 asm volatile("" ::: "memory");
; #pragma unroll
;                 for (int bj = 0; bj < 2; ++bj) { const u32x4 ga = bj ? ga1 : ga0, gb = bj ? gb1 : gb0;
;                     const f32x4 a0 = UNPK0(ga) + ba[bj][0], a1 = UNPK1(ga) + ba[bj][1], b0 = UNPK0(gb) + bb[bj][0], b1 = UNPK1(gb) + bb[bj][1];
; #pragma unroll
;                     for (int k = 0; k < 4; ++k) { acc[ai][bj][m][0][k] *= (1.0f + eneg(b0[k])) * __builtin_amdgcn_rcpf(1.0f + eneg(a0[k]));
;                                                   acc[ai][bj][m][1][k] *= (1.0f + eneg(b1[k])) * __builtin_amdgcn_rcpf(1.0f + eneg(a1[k])); } } }
	v_fma_f32 v176, v180, s89, v148
	v_exp_f32_e32 v180, v174
	v_fma_f32 v177, v177, s89, v136
	v_fma_f32 v175, v175, s89, v145
	v_med3_f32 v177, v177, s85, v226
	v_exp_f32_e32 v177, v177
	v_med3_f32 v175, v175, s85, v226
	v_med3_f32 v174, v176, s85, v226
	v_add_f32_e32 v176, 1.0, v180
	v_fma_f32 v180, v227, s89, v140
	v_exp_f32_e32 v227, v175
	v_fma_f32 v189, v189, s89, v149
	v_add_f32_e32 v177, 1.0, v177
	v_med3_f32 v175, v189, s85, v226
	v_exp_f32_e32 v166, v166
	v_exp_f32_e32 v167, v167
	v_exp_f32_e32 v174, v174
	v_exp_f32_e32 v175, v175
	v_rcp_f32_e32 v238, v177
	v_add_f32_e32 v177, 1.0, v227
	v_rcp_f32_e32 v168, v168
	v_rcp_f32_e32 v169, v169
	v_rcp_f32_e32 v176, v176
	v_rcp_f32_e32 v177, v177
	v_pk_add_f32 v[174:175], v[174:175], 1.0 op_sel_hi:[1,0]
	v_pk_add_f32 v[166:167], v[166:167], 1.0 op_sel_hi:[1,0]
	v_and_b32_e32 v181, 0xffff0000, v181
	v_pk_mul_f32 v[166:167], v[168:169], v[166:167]
	v_pk_mul_f32 v[168:169], v[176:177], v[174:175]
	v_pk_mul_f32 v[76:77], v[76:77], v[168:169]
	v_fma_f32 v169, v181, s89, v137
	v_med3_f32 v173, v173, s85, v226
	v_med3_f32 v169, v169, s85, v226
	v_exp_f32_e32 v173, v173
	v_exp_f32_e32 v169, v169
	v_fma_f32 v170, v170, s89, v138
	v_fma_f32 v171, v171, s89, v139
	v_fma_f32 v168, v239, s89, v141
	v_med3_f32 v170, v170, s85, v226
	v_med3_f32 v171, v171, s85, v226
	v_med3_f32 v180, v180, s85, v226
	v_med3_f32 v168, v168, s85, v226
	v_exp_f32_e32 v170, v170
	v_exp_f32_e32 v171, v171
	v_add_f32_e32 v173, 1.0, v173
	v_exp_f32_e32 v180, v180
	v_exp_f32_e32 v181, v168
	v_pk_mul_f32 v[74:75], v[74:75], v[166:167]
	v_add_f32_e32 v166, 1.0, v169
	v_rcp_f32_e32 v173, v173
	v_rcp_f32_e32 v239, v166
	v_pk_add_f32 v[166:167], v[180:181], 1.0 op_sel_hi:[1,0]
	v_pk_add_f32 v[168:169], v[170:171], 1.0 op_sel_hi:[1,0]
	v_pk_mul_f32 v[166:167], v[238:239], v[166:167]
	v_pk_mul_f32 v[168:169], v[172:173], v[168:169]
	v_pk_mul_f32 v[72:73], v[72:73], v[166:167]
	v_pk_mul_f32 v[70:71], v[70:71], v[168:169]
	global_load_dwordx4 v[174:177], v[178:179], off offset:2048
	s_nop 0
	global_load_dwordx4 v[178:181], v[178:179], off offset:3072
	s_nop 0
	global_load_dwordx4 v[166:169], v[236:237], off offset:2048
	global_load_dwordx4 v[170:173], v[236:237], off offset:3072
	s_waitcnt vmcnt(7)
	ds_write_b128 v3, v[190:193]
	s_waitcnt vmcnt(6)
	ds_write_b128 v3, v[194:197] offset:1152
	ds_read_b128 v[190:193], v188
	ds_read_b128 v[194:197], v188 offset:64
	s_waitcnt vmcnt(5)
	ds_write_b128 v3, v[228:231]
	s_waitcnt vmcnt(4)
	ds_write_b128 v3, v[232:235] offset:1152
	ds_read_b128 v[228:231], v188
	ds_read_b128 v[232:235], v188 offset:64
	s_waitcnt lgkmcnt(5)
	v_lshlrev_b32_e32 v189, 16, v190
	v_fma_f32 v189, v189, s89, v158
	v_med3_f32 v189, v189, s85, v226
	v_lshlrev_b32_e32 v236, 16, v191
	v_and_b32_e32 v237, 0xffff0000, v191
	v_lshlrev_b32_e32 v191, 16, v192
	v_exp_f32_e32 v189, v189
	v_fma_f32 v191, v191, s89, v150
	v_med3_f32 v191, v191, s85, v226
	v_and_b32_e32 v227, 0xffff0000, v190
	v_lshlrev_b32_e32 v239, 16, v193
	v_and_b32_e32 v241, 0xffff0000, v193
	s_waitcnt lgkmcnt(1)
	v_lshlrev_b32_e32 v190, 16, v228
	v_and_b32_e32 v193, 0xffff0000, v228
	v_lshlrev_b32_e32 v228, 16, v230
	v_add_f32_e32 v189, 1.0, v189
	v_exp_f32_e32 v191, v191
	v_and_b32_e32 v238, 0xffff0000, v192
	v_rcp_f32_e32 v192, v189
	v_fma_f32 v189, v228, s89, v154
	v_med3_f32 v189, v189, s85, v226
	v_exp_f32_e32 v228, v189
	v_add_f32_e32 v189, 1.0, v191
	v_fma_f32 v191, v227, s89, v159
	v_med3_f32 v191, v191, s85, v226
	v_lshlrev_b32_e32 v240, 16, v229
	v_and_b32_e32 v242, 0xffff0000, v229
	v_and_b32_e32 v229, 0xffff0000, v230
	v_rcp_f32_e32 v230, v189
	v_fma_f32 v189, v193, s89, v163
	v_exp_f32_e32 v193, v191
	v_fma_f32 v227, v238, s89, v151
	v_med3_f32 v189, v189, s85, v226
	v_med3_f32 v227, v227, s85, v226
	v_exp_f32_e32 v191, v189
	v_add_f32_e32 v189, 1.0, v193
	v_exp_f32_e32 v227, v227
	v_rcp_f32_e32 v193, v189
	v_fma_f32 v189, v229, s89, v155
	v_med3_f32 v189, v189, s85, v226
	v_exp_f32_e32 v229, v189
	v_add_f32_e32 v189, 1.0, v227
	v_fma_f32 v227, v236, s89, v160
	v_med3_f32 v227, v227, s85, v226
	v_exp_f32_e32 v227, v227
	v_lshlrev_b32_e32 v243, 16, v231
	v_and_b32_e32 v244, 0xffff0000, v231
	v_rcp_f32_e32 v231, v189
	v_fma_f32 v189, v240, s89, v164
	v_med3_f32 v189, v189, s85, v226
	v_exp_f32_e32 v236, v189
	v_add_f32_e32 v189, 1.0, v227
	v_fma_f32 v227, v239, s89, v152
	v_med3_f32 v227, v227, s85, v226
	v_exp_f32_e32 v227, v227
	v_fma_f32 v237, v237, s89, v161
	v_rcp_f32_e32 v238, v189
	v_fma_f32 v189, v243, s89, v156
	v_med3_f32 v237, v237, s85, v226
	v_med3_f32 v189, v189, s85, v226
	v_exp_f32_e32 v239, v237
	v_fma_f32 v190, v190, s89, v162
	v_exp_f32_e32 v240, v189
	v_add_f32_e32 v189, 1.0, v227
	v_fma_f32 v227, v242, s89, v165
	v_med3_f32 v190, v190, s85, v226
	v_med3_f32 v227, v227, s85, v226
	v_exp_f32_e32 v190, v190
	v_exp_f32_e32 v237, v227
	v_rcp_f32_e32 v242, v189
	v_add_f32_e32 v189, 1.0, v239
	v_rcp_f32_e32 v239, v189
	v_pk_add_f32 v[236:237], v[236:237], 1.0 op_sel_hi:[1,0]
	v_pk_add_f32 v[190:191], v[190:191], 1.0 op_sel_hi:[1,0]
	v_fma_f32 v189, v244, s89, v157
	v_pk_mul_f32 v[190:191], v[192:193], v[190:191]
	v_pk_mul_f32 v[192:193], v[238:239], v[236:237]
	v_pk_mul_f32 v[68:69], v[68:69], v[192:193]
	v_fma_f32 v192, v241, s89, v153
	v_med3_f32 v192, v192, s85, v226
	v_exp_f32_e32 v192, v192
	v_med3_f32 v189, v189, s85, v226
	v_exp_f32_e32 v241, v189
	v_pk_mul_f32 v[66:67], v[66:67], v[190:191]
	v_add_f32_e32 v189, 1.0, v192
	v_rcp_f32_e32 v243, v189
	v_lshlrev_b32_e32 v189, 16, v194
	v_fma_f32 v189, v189, s89, v142
	v_pk_add_f32 v[192:193], v[228:229], 1.0 op_sel_hi:[1,0]
	v_pk_mul_f32 v[192:193], v[230:231], v[192:193]
	v_med3_f32 v189, v189, s85, v226
	v_pk_mul_f32 v[62:63], v[62:63], v[192:193]
	v_lshlrev_b32_e32 v193, 16, v196
	v_exp_f32_e32 v189, v189
	v_fma_f32 v193, v193, s89, v134
	v_pk_add_f32 v[190:191], v[240:241], 1.0 op_sel_hi:[1,0]
	v_pk_mul_f32 v[190:191], v[242:243], v[190:191]
	v_med3_f32 v193, v193, s85, v226
	v_pk_mul_f32 v[64:65], v[64:65], v[190:191]
	v_and_b32_e32 v191, 0xffff0000, v194
	s_waitcnt lgkmcnt(0)
; #define UNPK0(q_) ((f32x4){bf_lo((q_).x), bf_hi((q_).x), bf_lo((q_).y), bf_hi((q_).y)})
; #define UNPK1(q_) ((f32x4){bf_lo((q_).z), bf_hi((q_).z), bf_lo((q_).w), bf_hi((q_).w)})
;     static __device__ __forceinline__ float eneg(float g) { return __builtin_amdgcn_exp2f(-1.4426950408889634f * fminf(fmaxf(g, -30.f), 30.f)); }
;     __device__ __forceinline__ void mid(f32x4 (&acc)[2][2][4][2], const Unit& u, int wr, int wc, int fr, int fq) const {
;     ...
;             for (int m = 2 * (am & 1); m < 2 * (am & 1) + 2; ++m) {
;                 pa.stage(ra[m][0], ra[m][1]); const u32x4 ga0 = pa.get(0), ga1 = pa.get(1);
;                 asm volatile("" ::: "memory");
;                 pb.stage(rb[m][0], rb[m][1]); const u32x4 gb0 = pb.get(0), gb1 = pb.get(1);
;                 asm volatile("" ::: "memory");
; #pragma unroll
;                 for (int bj = 0; bj < 2; ++bj) { const u32x4 ga = bj ? ga1 : ga0, gb = bj ? gb1 : gb0;
;                     const f32x4 a0 = UNPK0(ga) + ba[bj][0], a1 = UNPK1(ga) + ba[bj][1], b0 = UNPK0(gb) + bb[bj][0], b1 = UNPK1(gb) + bb[bj][1];
; #pragma unroll
;                     for (int k = 0; k < 4; ++k) { acc[ai][bj][m][0][k] *= (1.0f + eneg(b0[k])) * __builtin_amdgcn_rcpf(1.0f + eneg(a0[k]));
;                                                   acc[ai][bj][m][1][k] *= (1.0f + eneg(b1[k])) * __builtin_amdgcn_rcpf(1.0f + eneg(a1[k])); } } }
	v_lshlrev_b32_e32 v194, 16, v234
	v_add_f32_e32 v189, 1.0, v189
	v_exp_f32_e32 v193, v193
	v_rcp_f32_e32 v192, v189
	v_fma_f32 v189, v194, s89, v138
	v_fma_f32 v191, v191, s89, v143
	v_med3_f32 v189, v189, s85, v226
	v_med3_f32 v191, v191, s85, v226
	v_lshlrev_b32_e32 v227, 16, v195
	v_and_b32_e32 v229, 0xffff0000, v195
	v_and_b32_e32 v195, 0xffff0000, v196
	v_lshlrev_b32_e32 v231, 16, v197
	v_and_b32_e32 v236, 0xffff0000, v197
	v_and_b32_e32 v197, 0xffff0000, v232
	v_exp_f32_e32 v194, v189
	v_add_f32_e32 v189, 1.0, v193
	v_exp_f32_e32 v193, v191
	v_rcp_f32_e32 v196, v189
	v_fma_f32 v189, v197, s89, v147
	v_fma_f32 v195, v195, s89, v135
	v_med3_f32 v189, v189, s85, v226
	v_med3_f32 v195, v195, s85, v226
	v_and_b32_e32 v230, 0xffff0000, v234
	v_exp_f32_e32 v191, v189
	v_add_f32_e32 v189, 1.0, v193
	v_exp_f32_e32 v197, v195
	v_rcp_f32_e32 v193, v189
	v_fma_f32 v189, v230, s89, v139
	v_fma_f32 v227, v227, s89, v144
	v_med3_f32 v189, v189, s85, v226
	v_med3_f32 v227, v227, s85, v226
	v_lshlrev_b32_e32 v228, 16, v233
	v_exp_f32_e32 v195, v189
	v_add_f32_e32 v189, 1.0, v197
	v_exp_f32_e32 v227, v227
	v_rcp_f32_e32 v197, v189
	v_fma_f32 v189, v228, s89, v148
	v_med3_f32 v189, v189, s85, v226
	v_exp_f32_e32 v228, v189
	v_add_f32_e32 v189, 1.0, v227
	v_fma_f32 v227, v231, s89, v136
	v_med3_f32 v227, v227, s85, v226
	v_lshlrev_b32_e32 v190, 16, v232
	v_lshlrev_b32_e32 v232, 16, v235
	v_exp_f32_e32 v227, v227
	v_fma_f32 v229, v229, s89, v145
	v_rcp_f32_e32 v230, v189
	v_fma_f32 v189, v232, s89, v140
	v_med3_f32 v229, v229, s85, v226
	v_and_b32_e32 v233, 0xffff0000, v233
	v_med3_f32 v189, v189, s85, v226
	v_exp_f32_e32 v231, v229
	v_fma_f32 v190, v190, s89, v146
	v_exp_f32_e32 v232, v189
	v_add_f32_e32 v189, 1.0, v227
	v_fma_f32 v227, v233, s89, v149
	v_med3_f32 v190, v190, s85, v226
	v_med3_f32 v227, v227, s85, v226
	v_exp_f32_e32 v190, v190
	v_exp_f32_e32 v229, v227
	v_rcp_f32_e32 v234, v189
	v_add_f32_e32 v189, 1.0, v231
	v_rcp_f32_e32 v231, v189
	v_pk_add_f32 v[228:229], v[228:229], 1.0 op_sel_hi:[1,0]
	v_pk_add_f32 v[190:191], v[190:191], 1.0 op_sel_hi:[1,0]
	v_and_b32_e32 v235, 0xffff0000, v235
	v_pk_mul_f32 v[190:191], v[192:193], v[190:191]
	v_pk_mul_f32 v[192:193], v[230:231], v[228:229]
	v_fma_f32 v189, v235, s89, v141
	v_pk_mul_f32 v[60:61], v[60:61], v[192:193]
	v_fma_f32 v192, v236, s89, v137
	v_med3_f32 v192, v192, s85, v226
	v_exp_f32_e32 v192, v192
	v_med3_f32 v189, v189, s85, v226
	v_exp_f32_e32 v233, v189
	v_add_f32_e32 v189, 1.0, v192
	v_rcp_f32_e32 v235, v189
	s_waitcnt vmcnt(3)
	ds_write_b128 v3, v[174:177]
	s_waitcnt vmcnt(2)
	ds_write_b128 v3, v[178:181] offset:1152
	ds_read_b128 v[174:177], v188
	ds_read_b128 v[178:181], v188 offset:64
	s_waitcnt vmcnt(1)
	ds_write_b128 v3, v[166:169]
	s_waitcnt vmcnt(0)
	ds_write_b128 v3, v[170:173] offset:1152
	ds_read_b128 v[166:169], v188
	ds_read_b128 v[170:173], v188 offset:64
	v_pk_mul_f32 v[58:59], v[58:59], v[190:191]
	v_pk_add_f32 v[190:191], v[232:233], 1.0 op_sel_hi:[1,0]
	s_waitcnt lgkmcnt(5)
	v_lshlrev_b32_e32 v189, 16, v174
	v_pk_mul_f32 v[190:191], v[234:235], v[190:191]
	s_waitcnt lgkmcnt(1)
	v_lshlrev_b32_e32 v227, 16, v169
	v_pk_mul_f32 v[56:57], v[56:57], v[190:191]
	v_and_b32_e32 v190, 0xffff0000, v174
	v_lshlrev_b32_e32 v174, 16, v176
	v_and_b32_e32 v228, 0xffff0000, v169
	v_fma_f32 v169, v174, s89, v150
	v_pk_add_f32 v[192:193], v[194:195], 1.0 op_sel_hi:[1,0]
	v_pk_mul_f32 v[192:193], v[196:197], v[192:193]
	v_med3_f32 v169, v169, s85, v226
	v_pk_mul_f32 v[54:55], v[54:55], v[192:193]
	v_lshlrev_b32_e32 v191, 16, v175
	v_and_b32_e32 v193, 0xffff0000, v175
	v_and_b32_e32 v175, 0xffff0000, v176
	v_lshlrev_b32_e32 v192, 16, v167
	v_and_b32_e32 v196, 0xffff0000, v167
	v_lshlrev_b32_e32 v167, 16, v168
	v_exp_f32_e32 v169, v169
	v_fma_f32 v167, v167, s89, v154
	v_fma_f32 v175, v175, s89, v151
	v_med3_f32 v167, v167, s85, v226
	v_med3_f32 v175, v175, s85, v226
	v_and_b32_e32 v197, 0xffff0000, v168
	v_fma_f32 v168, v189, s89, v158
	v_exp_f32_e32 v174, v167
	v_add_f32_e32 v167, 1.0, v169
	v_fma_f32 v169, v190, s89, v159
	v_exp_f32_e32 v189, v175
	v_fma_f32 v190, v191, s89, v160
	v_lshlrev_b32_e32 v194, 16, v177
	v_and_b32_e32 v195, 0xffff0000, v177
	v_lshlrev_b32_e32 v176, 16, v166
	v_and_b32_e32 v177, 0xffff0000, v166
	v_med3_f32 v190, v190, s85, v226
	v_fma_f32 v166, v176, s89, v162
	v_rcp_f32_e32 v176, v167
	v_fma_f32 v167, v177, s89, v163
	v_fma_f32 v177, v197, s89, v155
	v_exp_f32_e32 v191, v190
	v_med3_f32 v175, v177, s85, v226
	v_add_f32_e32 v177, 1.0, v189
	v_fma_f32 v189, v192, s89, v164
	v_med3_f32 v189, v189, s85, v226
	v_exp_f32_e32 v190, v189
	v_add_f32_e32 v189, 1.0, v191
	v_fma_f32 v191, v194, s89, v152
	v_med3_f32 v191, v191, s85, v226
	v_exp_f32_e32 v191, v191
	v_fma_f32 v193, v193, s89, v161
	v_rcp_f32_e32 v192, v189
	v_fma_f32 v189, v227, s89, v156
	v_med3_f32 v168, v168, s85, v226
	v_med3_f32 v169, v169, s85, v226
	v_med3_f32 v193, v193, s85, v226
	v_exp_f32_e32 v168, v168
	v_exp_f32_e32 v169, v169
	v_med3_f32 v189, v189, s85, v226
	v_exp_f32_e32 v193, v193
	v_exp_f32_e32 v194, v189
	v_add_f32_e32 v189, 1.0, v191
	v_fma_f32 v191, v196, s89, v165
	v_med3_f32 v166, v166, s85, v226
	v_med3_f32 v167, v167, s85, v226
	v_med3_f32 v191, v191, s85, v226
	v_exp_f32_e32 v166, v166
	v_add_f32_e32 v168, 1.0, v168
	v_exp_f32_e32 v167, v167
	v_add_f32_e32 v169, 1.0, v169
	v_exp_f32_e32 v191, v191
	v_rcp_f32_e32 v196, v189
	v_add_f32_e32 v189, 1.0, v193
	v_rcp_f32_e32 v168, v168
	v_rcp_f32_e32 v169, v169
	v_rcp_f32_e32 v193, v189
	v_pk_add_f32 v[190:191], v[190:191], 1.0 op_sel_hi:[1,0]
	v_pk_add_f32 v[166:167], v[166:167], 1.0 op_sel_hi:[1,0]
	v_pk_mul_f32 v[166:167], v[168:169], v[166:167]
; #define UNPK0(q_) ((f32x4){bf_lo((q_).x), bf_hi((q_).x), bf_lo((q_).y), bf_hi((q_).y)})
; #define UNPK1(q_) ((f32x4){bf_lo((q_).z), bf_hi((q_).z), bf_lo((q_).w), bf_hi((q_).w)})
;     static __device__ __forceinline__ float eneg(float g) { return __builtin_amdgcn_exp2f(-1.4426950408889634f * fminf(fmaxf(g, -30.f), 30.f)); }
;     __device__ __forceinline__ void mid(f32x4 (&acc)[2][2][4][2], const Unit& u, int wr, int wc, int fr, int fq) const {
;     ...
;         for (int am = 0; am < 4; ++am) { const int ai = am >> 1;
;             u32x4 ra[4][2], rb[4][2];
; #pragma unroll
;             for (int m = 2 * (am & 1); m < 2 * (am & 1) + 2; ++m) { pa.fetch(ai, m, ra[m][0], ra[m][1]); pb.fetch(ai, m, rb[m][0], rb[m][1]); }
;             asm volatile("" ::: "memory");
; #pragma unroll
;             for (int m = 2 * (am & 1); m < 2 * (am & 1) + 2; ++m) {
;                 pa.stage(ra[m][0], ra[m][1]); const u32x4 ga0 = pa.get(0), ga1 = pa.get(1);
;                 asm volatile("" ::: "memory");
;                 pb.stage(rb[m][0], rb[m][1]); const u32x4 gb0 = pb.get(0), gb1 = pb.get(1);
;                 asm volatile("" ::: "memory");
; #pragma unroll
;                 for (int bj = 0; bj < 2; ++bj) { const u32x4 ga = bj ? ga1 : ga0, gb = bj ? gb1 : gb0;
;                     const f32x4 a0 = UNPK0(ga) + ba[bj][0], a1 = UNPK1(ga) + ba[bj][1], b0 = UNPK0(gb) + bb[bj][0], b1 = UNPK1(gb) + bb[bj][1];
; #pragma unroll
;                     for (int k = 0; k < 4; ++k) { acc[ai][bj][m][0][k] *= (1.0f + eneg(b0[k])) * __builtin_amdgcn_rcpf(1.0f + eneg(a0[k]));
;                                                   acc[ai][bj][m][1][k] *= (1.0f + eneg(b1[k])) * __builtin_amdgcn_rcpf(1.0f + eneg(a1[k])); } } }
	v_pk_mul_f32 v[168:169], v[192:193], v[190:191]
	v_pk_mul_f32 v[50:51], v[50:51], v[166:167]
	v_pk_mul_f32 v[52:53], v[52:53], v[168:169]
	v_fma_f32 v169, v195, s89, v153
	v_med3_f32 v169, v169, s85, v226
	v_exp_f32_e32 v169, v169
	v_fma_f32 v168, v228, s89, v157
	v_med3_f32 v168, v168, s85, v226
	v_exp_f32_e32 v195, v168
	v_add_f32_e32 v166, 1.0, v169
	v_rcp_f32_e32 v197, v166
	v_exp_f32_e32 v175, v175
	v_pk_add_f32 v[166:167], v[194:195], 1.0 op_sel_hi:[1,0]
	v_rcp_f32_e32 v177, v177
	v_pk_mul_f32 v[166:167], v[196:197], v[166:167]
	global_load_dwordx4 v[190:193], v[186:187], off
	global_load_dwordx4 v[194:197], v[186:187], off offset:1024
	global_load_dwordx4 v[228:231], v[4:5], off
	global_load_dwordx4 v[232:235], v[4:5], off offset:1024
	v_pk_add_f32 v[168:169], v[174:175], 1.0 op_sel_hi:[1,0]
	v_pk_mul_f32 v[48:49], v[48:49], v[166:167]
	v_pk_mul_f32 v[168:169], v[176:177], v[168:169]
	v_lshlrev_b32_e32 v166, 16, v178
	v_pk_mul_f32 v[46:47], v[46:47], v[168:169]
	v_lshlrev_b32_e32 v169, 16, v180
	v_fma_f32 v169, v169, s89, v134
	v_and_b32_e32 v167, 0xffff0000, v178
	v_fma_f32 v166, v166, s89, v142
	v_med3_f32 v169, v169, s85, v226
	v_fma_f32 v167, v167, s89, v143
	v_med3_f32 v166, v166, s85, v226
	v_exp_f32_e32 v169, v169
	v_lshlrev_b32_e32 v174, 16, v179
	v_and_b32_e32 v175, 0xffff0000, v179
	v_and_b32_e32 v176, 0xffff0000, v180
	v_lshlrev_b32_e32 v177, 16, v181
	v_and_b32_e32 v179, 0xffff0000, v181
	s_waitcnt lgkmcnt(0)
	v_lshlrev_b32_e32 v168, 16, v170
	v_and_b32_e32 v178, 0xffff0000, v170
	v_lshlrev_b32_e32 v180, 16, v171
	v_and_b32_e32 v181, 0xffff0000, v171
	v_lshlrev_b32_e32 v170, 16, v172
	v_and_b32_e32 v171, 0xffff0000, v172
	v_exp_f32_e32 v172, v166
	v_med3_f32 v167, v167, s85, v226
	v_lshlrev_b32_e32 v189, 16, v173
	v_and_b32_e32 v227, 0xffff0000, v173
	v_exp_f32_e32 v173, v167
	v_fma_f32 v177, v177, s89, v136
	v_fma_f32 v174, v174, s89, v144
	v_fma_f32 v175, v175, s89, v145
	v_fma_f32 v168, v168, s89, v146
	v_add_f32_e32 v169, 1.0, v169
	v_med3_f32 v177, v177, s85, v226
	v_med3_f32 v166, v168, s85, v226
	v_add_f32_e32 v168, 1.0, v172
	v_rcp_f32_e32 v172, v169
	v_fma_f32 v169, v178, s89, v147
	v_med3_f32 v174, v174, s85, v226
	v_exp_f32_e32 v177, v177
	v_med3_f32 v175, v175, s85, v226
	v_med3_f32 v167, v169, s85, v226
	v_add_f32_e32 v169, 1.0, v173
	v_fma_f32 v173, v176, s89, v135
	v_fma_f32 v176, v180, s89, v148
	v_exp_f32_e32 v178, v174
	v_fma_f32 v180, v181, s89, v149
	v_exp_f32_e32 v181, v175
	v_med3_f32 v174, v176, s85, v226
	v_add_f32_e32 v177, 1.0, v177
	v_med3_f32 v175, v180, s85, v226
	v_exp_f32_e32 v166, v166
	v_exp_f32_e32 v167, v167
	v_exp_f32_e32 v174, v174
	v_add_f32_e32 v176, 1.0, v178
	v_exp_f32_e32 v175, v175
	v_rcp_f32_e32 v180, v177
	v_add_f32_e32 v177, 1.0, v181
	v_rcp_f32_e32 v168, v168
	v_rcp_f32_e32 v169, v169
	v_rcp_f32_e32 v176, v176
	v_rcp_f32_e32 v177, v177
	v_pk_add_f32 v[174:175], v[174:175], 1.0 op_sel_hi:[1,0]
	v_pk_add_f32 v[166:167], v[166:167], 1.0 op_sel_hi:[1,0]
	v_pk_mul_f32 v[166:167], v[168:169], v[166:167]
	v_pk_mul_f32 v[168:169], v[176:177], v[174:175]
	v_med3_f32 v173, v173, s85, v226
	v_pk_mul_f32 v[44:45], v[44:45], v[168:169]
	v_fma_f32 v169, v179, s89, v137
	v_med3_f32 v169, v169, s85, v226
	v_exp_f32_e32 v173, v173
	v_exp_f32_e32 v169, v169
	v_fma_f32 v170, v170, s89, v138
	v_fma_f32 v171, v171, s89, v139
	v_fma_f32 v178, v189, s89, v140
	v_fma_f32 v168, v227, s89, v141
	v_med3_f32 v170, v170, s85, v226
	v_med3_f32 v171, v171, s85, v226
	v_med3_f32 v178, v178, s85, v226
	v_med3_f32 v168, v168, s85, v226
	v_exp_f32_e32 v170, v170
	v_exp_f32_e32 v171, v171
	v_add_f32_e32 v173, 1.0, v173
	v_exp_f32_e32 v178, v178
	v_exp_f32_e32 v179, v168
	v_pk_mul_f32 v[42:43], v[42:43], v[166:167]
	v_add_f32_e32 v166, 1.0, v169
	v_rcp_f32_e32 v173, v173
	v_rcp_f32_e32 v181, v166
	v_pk_add_f32 v[166:167], v[178:179], 1.0 op_sel_hi:[1,0]
	v_pk_add_f32 v[168:169], v[170:171], 1.0 op_sel_hi:[1,0]
	v_pk_mul_f32 v[166:167], v[180:181], v[166:167]
	v_pk_mul_f32 v[168:169], v[172:173], v[168:169]
	v_pk_mul_f32 v[40:41], v[40:41], v[166:167]
	v_pk_mul_f32 v[38:39], v[38:39], v[168:169]
	global_load_dwordx4 v[174:177], v[186:187], off offset:2048
	global_load_dwordx4 v[178:181], v[186:187], off offset:3072
	global_load_dwordx4 v[166:169], v[4:5], off offset:2048
	global_load_dwordx4 v[170:173], v[4:5], off offset:3072
	s_waitcnt vmcnt(7)
	ds_write_b128 v3, v[190:193]
	s_waitcnt vmcnt(6)
	ds_write_b128 v3, v[194:197] offset:1152
	ds_read_b128 v[190:193], v188
	ds_read_b128 v[194:197], v188 offset:64
	s_waitcnt vmcnt(5)
	ds_write_b128 v3, v[228:231]
	s_waitcnt vmcnt(4)
	ds_write_b128 v3, v[232:235] offset:1152
	ds_read_b128 v[228:231], v188
	ds_read_b128 v[232:235], v188 offset:64
	s_waitcnt lgkmcnt(5)
	v_lshlrev_b32_e32 v187, 16, v192
	v_lshlrev_b32_e32 v4, 16, v190
	v_fma_f32 v187, v187, s89, v150
	v_fma_f32 v4, v4, s89, v158
	v_med3_f32 v187, v187, s85, v226
	v_med3_f32 v4, v4, s85, v226
	v_exp_f32_e32 v187, v187
	v_and_b32_e32 v5, 0xffff0000, v190
	v_lshlrev_b32_e32 v189, 16, v191
	v_and_b32_e32 v227, 0xffff0000, v191
	v_and_b32_e32 v191, 0xffff0000, v192
	v_exp_f32_e32 v192, v4
	v_fma_f32 v5, v5, s89, v159
	s_waitcnt lgkmcnt(1)
; #define UNPK0(q_) ((f32x4){bf_lo((q_).x), bf_hi((q_).x), bf_lo((q_).y), bf_hi((q_).y)})
; #define UNPK1(q_) ((f32x4){bf_lo((q_).z), bf_hi((q_).z), bf_lo((q_).w), bf_hi((q_).w)})
;     static __device__ __forceinline__ float eneg(float g) { return __builtin_amdgcn_exp2f(-1.4426950408889634f * fminf(fmaxf(g, -30.f), 30.f)); }
;     __device__ __forceinline__ void mid(f32x4 (&acc)[2][2][4][2], const Unit& u, int wr, int wc, int fr, int fq) const {
;     ...
;                 for (int bj = 0; bj < 2; ++bj) { const u32x4 ga = bj ? ga1 : ga0, gb = bj ? gb1 : gb0;
;                     const f32x4 a0 = UNPK0(ga) + ba[bj][0], a1 = UNPK1(ga) + ba[bj][1], b0 = UNPK0(gb) + bb[bj][0], b1 = UNPK1(gb) + bb[bj][1];
; #pragma unroll
;                     for (int k = 0; k < 4; ++k) { acc[ai][bj][m][0][k] *= (1.0f + eneg(b0[k])) * __builtin_amdgcn_rcpf(1.0f + eneg(a0[k]));
;                                                   acc[ai][bj][m][1][k] *= (1.0f + eneg(b1[k])) * __builtin_amdgcn_rcpf(1.0f + eneg(a1[k])); } } }
	v_lshlrev_b32_e32 v186, 16, v228
	v_lshlrev_b32_e32 v236, 16, v193
	v_and_b32_e32 v237, 0xffff0000, v193
	v_and_b32_e32 v193, 0xffff0000, v228
	v_fma_f32 v186, v186, s89, v162
	v_add_f32_e32 v187, 1.0, v187
	v_med3_f32 v5, v5, s85, v226
	v_med3_f32 v4, v186, s85, v226
	v_add_f32_e32 v186, 1.0, v192
	v_rcp_f32_e32 v192, v187
	v_fma_f32 v187, v193, s89, v163
	v_exp_f32_e32 v193, v5
	v_fma_f32 v189, v189, s89, v160
	v_fma_f32 v191, v191, s89, v151
	v_med3_f32 v189, v189, s85, v226
	v_lshlrev_b32_e32 v190, 16, v230
	v_and_b32_e32 v230, 0xffff0000, v230
	v_med3_f32 v191, v191, s85, v226
	v_exp_f32_e32 v189, v189
	v_lshlrev_b32_e32 v238, 16, v231
	v_and_b32_e32 v239, 0xffff0000, v231
	v_med3_f32 v5, v187, s85, v226
	v_add_f32_e32 v187, 1.0, v193
	v_fma_f32 v193, v230, s89, v155
	v_exp_f32_e32 v230, v191
	v_fma_f32 v231, v236, s89, v152
	v_fma_f32 v227, v227, s89, v161
	v_med3_f32 v231, v231, s85, v226
	v_add_f32_e32 v189, 1.0, v189
	v_exp_f32_e32 v231, v231
	v_med3_f32 v227, v227, s85, v226
	v_lshlrev_b32_e32 v228, 16, v229
	v_and_b32_e32 v229, 0xffff0000, v229
	v_med3_f32 v191, v193, s85, v226
	v_add_f32_e32 v193, 1.0, v230
	v_rcp_f32_e32 v230, v189
	v_fma_f32 v189, v238, s89, v156
	v_exp_f32_e32 v227, v227
	v_fma_f32 v228, v228, s89, v164
	v_fma_f32 v229, v229, s89, v165
	v_med3_f32 v189, v189, s85, v226
	v_med3_f32 v228, v228, s85, v226
	v_exp_f32_e32 v236, v189
	v_add_f32_e32 v189, 1.0, v231
	v_med3_f32 v229, v229, s85, v226
	v_exp_f32_e32 v4, v4
	v_exp_f32_e32 v5, v5
	v_exp_f32_e32 v228, v228
	v_exp_f32_e32 v229, v229
	v_rcp_f32_e32 v238, v189
	v_add_f32_e32 v189, 1.0, v227
	v_rcp_f32_e32 v186, v186
	v_rcp_f32_e32 v187, v187
	v_rcp_f32_e32 v231, v189
	v_pk_add_f32 v[228:229], v[228:229], 1.0 op_sel_hi:[1,0]
	v_pk_add_f32 v[4:5], v[4:5], 1.0 op_sel_hi:[1,0]
	v_fma_f32 v190, v190, s89, v154
	v_pk_mul_f32 v[4:5], v[186:187], v[4:5]
	v_pk_mul_f32 v[186:187], v[230:231], v[228:229]
	v_pk_mul_f32 v[36:37], v[36:37], v[186:187]
	v_fma_f32 v187, v237, s89, v153
	v_med3_f32 v187, v187, s85, v226
	v_exp_f32_e32 v187, v187
	v_fma_f32 v186, v239, s89, v157
	v_med3_f32 v190, v190, s85, v226
	v_exp_f32_e32 v190, v190
	v_exp_f32_e32 v191, v191
	v_med3_f32 v186, v186, s85, v226
	v_rcp_f32_e32 v193, v193
	v_exp_f32_e32 v237, v186
	v_pk_mul_f32 v[34:35], v[34:35], v[4:5]
	v_add_f32_e32 v4, 1.0, v187
	v_rcp_f32_e32 v239, v4
	v_pk_add_f32 v[186:187], v[190:191], 1.0 op_sel_hi:[1,0]
	v_pk_add_f32 v[4:5], v[236:237], 1.0 op_sel_hi:[1,0]
	v_pk_mul_f32 v[186:187], v[192:193], v[186:187]
	v_pk_mul_f32 v[4:5], v[238:239], v[4:5]
	v_pk_mul_f32 v[30:31], v[30:31], v[186:187]
	v_lshlrev_b32_e32 v187, 16, v196
	v_pk_mul_f32 v[32:33], v[32:33], v[4:5]
	v_lshlrev_b32_e32 v4, 16, v194
	v_fma_f32 v187, v187, s89, v134
	v_fma_f32 v4, v4, s89, v142
	v_med3_f32 v187, v187, s85, v226
	v_med3_f32 v4, v4, s85, v226
	v_exp_f32_e32 v187, v187
	v_and_b32_e32 v5, 0xffff0000, v194
	v_exp_f32_e32 v192, v4
	v_fma_f32 v5, v5, s89, v143
	s_waitcnt lgkmcnt(0)
	v_lshlrev_b32_e32 v186, 16, v232
	v_lshlrev_b32_e32 v189, 16, v195
	v_and_b32_e32 v193, 0xffff0000, v232
	v_fma_f32 v186, v186, s89, v146
	v_add_f32_e32 v187, 1.0, v187
	v_med3_f32 v5, v5, s85, v226
	v_and_b32_e32 v191, 0xffff0000, v196
	v_med3_f32 v4, v186, s85, v226
	v_add_f32_e32 v186, 1.0, v192
	v_rcp_f32_e32 v192, v187
	v_fma_f32 v187, v193, s89, v147
	v_exp_f32_e32 v193, v5
	v_fma_f32 v189, v189, s89, v144
	v_fma_f32 v191, v191, s89, v135
	v_med3_f32 v189, v189, s85, v226
	v_lshlrev_b32_e32 v227, 16, v197
	v_and_b32_e32 v196, 0xffff0000, v234
	v_med3_f32 v191, v191, s85, v226
	v_exp_f32_e32 v189, v189
	v_med3_f32 v5, v187, s85, v226
	v_add_f32_e32 v187, 1.0, v193
	v_fma_f32 v193, v196, s89, v139
	v_exp_f32_e32 v196, v191
	v_fma_f32 v227, v227, s89, v136
	v_med3_f32 v227, v227, s85, v226
	v_and_b32_e32 v195, 0xffff0000, v195
	v_lshlrev_b32_e32 v228, 16, v235
	v_add_f32_e32 v189, 1.0, v189
	v_exp_f32_e32 v227, v227
	v_med3_f32 v191, v193, s85, v226
	v_add_f32_e32 v193, 1.0, v196
	v_rcp_f32_e32 v196, v189
	v_fma_f32 v189, v228, s89, v140
	v_fma_f32 v195, v195, s89, v145
	v_med3_f32 v189, v189, s85, v226
	v_med3_f32 v195, v195, s85, v226
	v_and_b32_e32 v229, 0xffff0000, v197
	v_lshlrev_b32_e32 v194, 16, v233
	v_and_b32_e32 v197, 0xffff0000, v233
	v_exp_f32_e32 v228, v189
	v_add_f32_e32 v189, 1.0, v227
	v_exp_f32_e32 v227, v195
	v_fma_f32 v194, v194, s89, v148
	v_fma_f32 v197, v197, s89, v149
	v_med3_f32 v194, v194, s85, v226
	v_med3_f32 v195, v197, s85, v226
	v_exp_f32_e32 v4, v4
	v_exp_f32_e32 v5, v5
	v_exp_f32_e32 v194, v194
	v_exp_f32_e32 v195, v195
	v_rcp_f32_e32 v230, v189
	v_add_f32_e32 v189, 1.0, v227
	v_rcp_f32_e32 v186, v186
	v_rcp_f32_e32 v187, v187
	v_rcp_f32_e32 v197, v189
	v_pk_add_f32 v[194:195], v[194:195], 1.0 op_sel_hi:[1,0]
	v_pk_add_f32 v[4:5], v[4:5], 1.0 op_sel_hi:[1,0]
	v_lshlrev_b32_e32 v190, 16, v234
	v_pk_mul_f32 v[4:5], v[186:187], v[4:5]
	v_pk_mul_f32 v[186:187], v[196:197], v[194:195]
	s_waitcnt vmcnt(3)
	ds_write_b128 v3, v[174:177]
	s_waitcnt vmcnt(2)
	ds_write_b128 v3, v[178:181] offset:1152
	v_fma_f32 v190, v190, s89, v138
	v_pk_mul_f32 v[28:29], v[28:29], v[186:187]
	v_fma_f32 v187, v229, s89, v137
	ds_read_b128 v[174:177], v188
	ds_read_b128 v[178:181], v188 offset:64
	v_med3_f32 v190, v190, s85, v226
	v_med3_f32 v187, v187, s85, v226
	v_and_b32_e32 v231, 0xffff0000, v235
	v_exp_f32_e32 v190, v190
	v_exp_f32_e32 v191, v191
	v_exp_f32_e32 v187, v187
	v_rcp_f32_e32 v193, v193
	v_fma_f32 v186, v231, s89, v141
	s_waitcnt vmcnt(1)
	ds_write_b128 v3, v[166:169]
	s_waitcnt vmcnt(0)
	ds_write_b128 v3, v[170:173] offset:1152
	s_waitcnt lgkmcnt(3)
; #define UNPK0(q_) ((f32x4){bf_lo((q_).x), bf_hi((q_).x), bf_lo((q_).y), bf_hi((q_).y)})
; #define UNPK1(q_) ((f32x4){bf_lo((q_).z), bf_hi((q_).z), bf_lo((q_).w), bf_hi((q_).w)})
;     static __device__ __forceinline__ float eneg(float g) { return __builtin_amdgcn_exp2f(-1.4426950408889634f * fminf(fmaxf(g, -30.f), 30.f)); }
;     __device__ __forceinline__ void mid(f32x4 (&acc)[2][2][4][2], const Unit& u, int wr, int wc, int fr, int fq) const {
;     ...
;                 for (int bj = 0; bj < 2; ++bj) { const u32x4 ga = bj ? ga1 : ga0, gb = bj ? gb1 : gb0;
;                     const f32x4 a0 = UNPK0(ga) + ba[bj][0], a1 = UNPK1(ga) + ba[bj][1], b0 = UNPK0(gb) + bb[bj][0], b1 = UNPK1(gb) + bb[bj][1];
; #pragma unroll
;                     for (int k = 0; k < 4; ++k) { acc[ai][bj][m][0][k] *= (1.0f + eneg(b0[k])) * __builtin_amdgcn_rcpf(1.0f + eneg(a0[k]));
;                                                   acc[ai][bj][m][1][k] *= (1.0f + eneg(b1[k])) * __builtin_amdgcn_rcpf(1.0f + eneg(a1[k])); } } }
	v_lshlrev_b32_e32 v3, 16, v174
	v_fma_f32 v3, v3, s89, v158
	v_med3_f32 v186, v186, s85, v226
	v_exp_f32_e32 v229, v186
	v_pk_mul_f32 v[26:27], v[26:27], v[4:5]
	v_add_f32_e32 v4, 1.0, v187
	v_pk_add_f32 v[186:187], v[190:191], 1.0 op_sel_hi:[1,0]
	v_med3_f32 v3, v3, s85, v226
	v_rcp_f32_e32 v231, v4
	v_pk_mul_f32 v[186:187], v[192:193], v[186:187]
	ds_read_b128 v[166:169], v188
	ds_read_b128 v[170:173], v188 offset:64
	v_exp_f32_e32 v3, v3
	v_pk_mul_f32 v[22:23], v[22:23], v[186:187]
	v_lshlrev_b32_e32 v186, 16, v176
	v_fma_f32 v150, v186, s89, v150
	v_pk_add_f32 v[4:5], v[228:229], 1.0 op_sel_hi:[1,0]
	v_pk_mul_f32 v[4:5], v[230:231], v[4:5]
	s_waitcnt lgkmcnt(1)
	v_lshlrev_b32_e32 v189, 16, v168
	v_add_f32_e32 v3, 1.0, v3
	v_med3_f32 v150, v150, s85, v226
	v_pk_mul_f32 v[24:25], v[24:25], v[4:5]
	v_and_b32_e32 v5, 0xffff0000, v174
	v_rcp_f32_e32 v158, v3
	v_fma_f32 v3, v189, s89, v154
	v_exp_f32_e32 v154, v150
	v_fma_f32 v5, v5, s89, v159
	v_med3_f32 v3, v3, s85, v226
	v_med3_f32 v5, v5, s85, v226
	v_lshlrev_b32_e32 v4, 16, v166
	v_and_b32_e32 v166, 0xffff0000, v166
	v_exp_f32_e32 v150, v3
	v_add_f32_e32 v3, 1.0, v154
	v_exp_f32_e32 v159, v5
	v_and_b32_e32 v176, 0xffff0000, v176
	v_rcp_f32_e32 v154, v3
	v_fma_f32 v3, v166, s89, v163
	v_fma_f32 v151, v176, s89, v151
	v_med3_f32 v3, v3, s85, v226
	v_and_b32_e32 v168, 0xffff0000, v168
	v_exp_f32_e32 v5, v3
	v_add_f32_e32 v3, 1.0, v159
	v_med3_f32 v151, v151, s85, v226
	v_lshlrev_b32_e32 v174, 16, v175
	v_rcp_f32_e32 v159, v3
	v_fma_f32 v3, v168, s89, v155
	v_exp_f32_e32 v155, v151
	v_fma_f32 v160, v174, s89, v160
	v_med3_f32 v3, v3, s85, v226
	v_med3_f32 v160, v160, s85, v226
	v_lshlrev_b32_e32 v188, 16, v167
	v_fma_f32 v4, v4, s89, v162
	v_exp_f32_e32 v151, v3
	v_add_f32_e32 v3, 1.0, v155
	v_exp_f32_e32 v162, v160
	v_lshlrev_b32_e32 v187, 16, v177
	v_rcp_f32_e32 v155, v3
	v_fma_f32 v3, v188, s89, v164
	v_fma_f32 v152, v187, s89, v152
	v_med3_f32 v3, v3, s85, v226
	v_and_b32_e32 v175, 0xffff0000, v175
	v_lshlrev_b32_e32 v190, 16, v169
	v_exp_f32_e32 v160, v3
	v_add_f32_e32 v3, 1.0, v162
	v_med3_f32 v152, v152, s85, v226
	v_rcp_f32_e32 v162, v3
	v_fma_f32 v3, v190, s89, v156
	v_exp_f32_e32 v156, v152
	v_fma_f32 v161, v175, s89, v161
	v_med3_f32 v161, v161, s85, v226
	v_and_b32_e32 v167, 0xffff0000, v167
	v_med3_f32 v3, v3, s85, v226
	v_exp_f32_e32 v163, v161
	v_and_b32_e32 v177, 0xffff0000, v177
	v_exp_f32_e32 v152, v3
	v_add_f32_e32 v3, 1.0, v156
	v_fma_f32 v156, v167, s89, v165
	v_fma_f32 v153, v177, s89, v153
	v_med3_f32 v156, v156, s85, v226
	v_and_b32_e32 v169, 0xffff0000, v169
	v_exp_f32_e32 v161, v156
	v_rcp_f32_e32 v156, v3
	v_add_f32_e32 v3, 1.0, v163
	v_med3_f32 v153, v153, s85, v226
	v_rcp_f32_e32 v163, v3
	v_fma_f32 v3, v169, s89, v157
	v_exp_f32_e32 v157, v153
	v_med3_f32 v4, v4, s85, v226
	v_med3_f32 v3, v3, s85, v226
	v_exp_f32_e32 v4, v4
	v_exp_f32_e32 v153, v3
	v_add_f32_e32 v3, 1.0, v157
	v_rcp_f32_e32 v157, v3
	v_lshlrev_b32_e32 v3, 16, v178
	v_fma_f32 v3, v3, s89, v142
	v_pk_add_f32 v[4:5], v[4:5], 1.0 op_sel_hi:[1,0]
	v_med3_f32 v3, v3, s85, v226
	v_pk_mul_f32 v[4:5], v[158:159], v[4:5]
	v_exp_f32_e32 v3, v3
	v_pk_mul_f32 v[18:19], v[18:19], v[4:5]
	v_pk_add_f32 v[4:5], v[152:153], 1.0 op_sel_hi:[1,0]
	v_lshlrev_b32_e32 v152, 16, v180
	v_pk_add_f32 v[160:161], v[160:161], 1.0 op_sel_hi:[1,0]
	v_fma_f32 v134, v152, s89, v134
	v_pk_mul_f32 v[158:159], v[162:163], v[160:161]
	v_pk_mul_f32 v[20:21], v[20:21], v[158:159]
	v_pk_mul_f32 v[4:5], v[156:157], v[4:5]
	s_waitcnt lgkmcnt(0)
	v_lshlrev_b32_e32 v159, 16, v172
	v_add_f32_e32 v3, 1.0, v3
	v_med3_f32 v134, v134, s85, v226
	v_pk_mul_f32 v[16:17], v[16:17], v[4:5]
	v_and_b32_e32 v5, 0xffff0000, v178
	v_rcp_f32_e32 v142, v3
	v_fma_f32 v3, v159, s89, v138
	v_exp_f32_e32 v138, v134
	v_fma_f32 v5, v5, s89, v143
	v_med3_f32 v3, v3, s85, v226
	v_med3_f32 v5, v5, s85, v226
	v_and_b32_e32 v156, 0xffff0000, v170
	v_exp_f32_e32 v134, v3
	v_add_f32_e32 v3, 1.0, v138
	v_exp_f32_e32 v143, v5
	v_and_b32_e32 v153, 0xffff0000, v180
	v_rcp_f32_e32 v138, v3
	v_fma_f32 v3, v156, s89, v147
	v_fma_f32 v135, v153, s89, v135
	v_pk_add_f32 v[150:151], v[150:151], 1.0 op_sel_hi:[1,0]
	v_med3_f32 v3, v3, s85, v226
	v_pk_mul_f32 v[150:151], v[154:155], v[150:151]
	v_and_b32_e32 v160, 0xffff0000, v172
	v_exp_f32_e32 v5, v3
	v_add_f32_e32 v3, 1.0, v143
	v_med3_f32 v135, v135, s85, v226
	v_pk_mul_f32 v[14:15], v[14:15], v[150:151]
	v_lshlrev_b32_e32 v150, 16, v179
	v_rcp_f32_e32 v143, v3
	v_fma_f32 v3, v160, s89, v139
	v_exp_f32_e32 v139, v135
	v_fma_f32 v144, v150, s89, v144
	v_lshlrev_b32_e32 v4, 16, v170
	v_med3_f32 v3, v3, s85, v226
	v_med3_f32 v144, v144, s85, v226
	v_lshlrev_b32_e32 v157, 16, v171
	v_fma_f32 v4, v4, s89, v146
	v_exp_f32_e32 v135, v3
	v_add_f32_e32 v3, 1.0, v139
	v_exp_f32_e32 v146, v144
	v_lshlrev_b32_e32 v154, 16, v181
	v_rcp_f32_e32 v139, v3
	v_fma_f32 v3, v157, s89, v148
	v_fma_f32 v136, v154, s89, v136
	v_med3_f32 v3, v3, s85, v226
	v_and_b32_e32 v151, 0xffff0000, v179
	v_lshlrev_b32_e32 v161, 16, v173
	v_exp_f32_e32 v144, v3
	v_add_f32_e32 v3, 1.0, v146
	v_med3_f32 v136, v136, s85, v226
	v_rcp_f32_e32 v146, v3
	v_fma_f32 v3, v161, s89, v140
	v_exp_f32_e32 v140, v136
	v_fma_f32 v145, v151, s89, v145
	v_med3_f32 v145, v145, s85, v226
	v_and_b32_e32 v158, 0xffff0000, v171
	v_med3_f32 v3, v3, s85, v226
	v_exp_f32_e32 v147, v145
	v_and_b32_e32 v155, 0xffff0000, v181
	v_exp_f32_e32 v136, v3
	v_add_f32_e32 v3, 1.0, v140
	v_fma_f32 v140, v158, s89, v149
	v_fma_f32 v137, v155, s89, v137
	v_med3_f32 v140, v140, s85, v226
	v_and_b32_e32 v162, 0xffff0000, v173
	v_exp_f32_e32 v145, v140
	v_rcp_f32_e32 v140, v3
	v_add_f32_e32 v3, 1.0, v147
	v_med3_f32 v137, v137, s85, v226
	v_rcp_f32_e32 v147, v3
	v_fma_f32 v3, v162, s89, v141
	v_exp_f32_e32 v141, v137
	v_med3_f32 v4, v4, s85, v226
	v_exp_f32_e32 v4, v4
	v_med3_f32 v3, v3, s85, v226
	v_exp_f32_e32 v137, v3
	v_add_f32_e32 v3, 1.0, v141
	v_rcp_f32_e32 v141, v3
	v_pk_add_f32 v[4:5], v[4:5], 1.0 op_sel_hi:[1,0]
	v_pk_add_f32 v[144:145], v[144:145], 1.0 op_sel_hi:[1,0]
	v_pk_mul_f32 v[4:5], v[142:143], v[4:5]
	v_pk_add_f32 v[134:135], v[134:135], 1.0 op_sel_hi:[1,0]
	v_pk_mul_f32 v[10:11], v[10:11], v[4:5]
	v_pk_add_f32 v[4:5], v[136:137], 1.0 op_sel_hi:[1,0]
	v_pk_mul_f32 v[142:143], v[146:147], v[144:145]
	v_pk_mul_f32 v[134:135], v[138:139], v[134:135]
	v_pk_mul_f32 v[4:5], v[140:141], v[4:5]
	v_pk_mul_f32 v[12:13], v[12:13], v[142:143]
	v_pk_mul_f32 v[8:9], v[8:9], v[4:5]
	v_pk_mul_f32 v[6:7], v[6:7], v[134:135]
	s_branch .LBB0_380

; __device__ __forceinline__ size_t tm_block(int pm, int ct, int nct) { return ((size_t)pm * nct + ct) * 32768; }
; #define UNPK0(q_) ((f32x4){bf_lo((q_).x), bf_hi((q_).x), bf_lo((q_).y), bf_hi((q_).y)})
; #define UNPK1(q_) ((f32x4){bf_lo((q_).z), bf_hi((q_).z), bf_lo((q_).w), bf_hi((q_).w)})
;     static __device__ __forceinline__ float eneg(float g) { return __builtin_amdgcn_exp2f(-1.4426950408889634f * fminf(fmaxf(g, -30.f), 30.f)); }
;     __device__ __forceinline__ void operator()(const f32x4 (&acc)[2][2][4][2], const Unit& u, int wr, int wc, int fr, int fq) const {
;         const int cb = u.pn * 4 + wc, col0 = cb * 64 + 8 * fq;
;         const PieceOut po(scr, O, tm_block(u.pm, cb, 16), wr, wc, fr, fq);
;         const PieceIn pb(scr, Z, tm_block(u.pm, gb_ct + cb, znct), wr, wc, fr, fq);
;         f32x4 bb[2][2];
; #pragma unroll
;         for (int bj = 0; bj < 2; ++bj) { bb[bj][0] = *(const f32x4*)(bg + 1024 + col0 + bj * 32); bb[bj][1] = *(const f32x4*)(bg + 1024 + col0 + bj * 32 + 4); }
;         u32x4 rb[2][4][2];
; #pragma unroll
;         for (int ai = 0; ai < 2; ++ai)
; #pragma unroll
;             for (int m = 0; m < 4; ++m) pb.fetch(ai, m, rb[ai][m][0], rb[ai][m][1]);
;         asm volatile("" ::: "memory");
; #pragma unroll
;         for (int ai = 0; ai < 2; ++ai)
; #pragma unroll
;             for (int m = 0; m < 4; ++m) {
;                 pb.stage(rb[ai][m][0], rb[ai][m][1]); const u32x4 gb0 = pb.get(0), gb1 = pb.get(1);
;                 asm volatile("" ::: "memory");
; #pragma unroll
;                 for (int bj = 0; bj < 2; ++bj) { const u32x4 gb = bj ? gb1 : gb0;
;                     const f32x4 b0 = UNPK0(gb) + bb[bj][0], b1 = UNPK1(gb) + bb[bj][1];
;                     f32x4 v0 = acc[ai][bj][m][0], v1 = acc[ai][bj][m][1];
; #pragma unroll
;                     for (int k = 0; k < 4; ++k) { v0[k] *= __builtin_amdgcn_rcpf(1.0f + eneg(b0[k])); v1[k] *= __builtin_amdgcn_rcpf(1.0f + eneg(b1[k])); }
.LBB0_385:
	s_ashr_i32 s27, s26, 31
	s_lshl_b64 s[0:1], s[26:27], 19
	s_add_u32 s19, s3, s0
	s_addc_u32 s21, s76, s1
	s_add_i32 s0, s44, 52
	s_mul_hi_i32 s1, s26, 0x44
	s_mulk_i32 s26, 0x44
	s_ashr_i32 s27, s0, 31
	s_add_u32 s0, s26, s0
	s_addc_u32 s1, s1, s27
	s_lshl_b64 s[0:1], s[0:1], 15
	v_lshl_add_u64 v[4:5], v[208:209], 0, s[0:1]
	global_load_dwordx4 v[228:231], v[4:5], off
	global_load_dwordx4 v[232:235], v[4:5], off offset:1024
	v_lshl_or_b32 v134, s44, 6, v219
	v_ashrrev_i32_e32 v135, 31, v134
	v_lshlrev_b64 v[134:135], 2, v[134:135]
	v_lshl_add_u64 v[136:137], s[16:17], 0, v[134:135]
	v_lshl_add_u64 v[134:135], s[42:43], 0, v[134:135]
	v_add_co_u32_e32 v134, vcc, s84, v134
	global_load_dwordx4 v[146:149], v[136:137], off
	s_nop 0
	v_addc_co_u32_e32 v135, vcc, 0, v135, vcc
	global_load_dwordx4 v[142:145], v[134:135], off offset:16
	global_load_dwordx4 v[138:141], v[136:137], off offset:128
	s_nop 0
	global_load_dwordx4 v[134:137], v[134:135], off offset:144
	s_nop 0
	global_load_dwordx4 v[236:239], v[4:5], off offset:2048
	global_load_dwordx4 v[240:243], v[4:5], off offset:3072
	v_add_co_u32_e32 v150, vcc, s84, v4
	v_add_u32_e32 v3, v224, v222
	s_nop 0
	v_addc_co_u32_e32 v151, vcc, 0, v5, vcc
	v_add_co_u32_e32 v152, vcc, s79, v4
	v_add_u32_e32 v227, v223, v220
	s_nop 0
	v_addc_co_u32_e32 v153, vcc, 0, v5, vcc
	v_add_co_u32_e32 v4, vcc, s86, v4
	s_ashr_i32 s45, s44, 31
	s_nop 0
	v_addc_co_u32_e32 v5, vcc, 0, v5, vcc
	global_load_dwordx4 v[190:193], v[150:151], off
	global_load_dwordx4 v[194:197], v[150:151], off offset:1024
	global_load_dwordx4 v[182:185], v[150:151], off offset:2048
	global_load_dwordx4 v[186:189], v[150:151], off offset:3072
	global_load_dwordx4 v[174:177], v[152:153], off offset:1024
	global_load_dwordx4 v[166:169], v[152:153], off offset:2048
	global_load_dwordx4 v[178:181], v[4:5], off offset:-4096
	global_load_dwordx4 v[170:173], v[152:153], off offset:3072
	global_load_dwordx4 v[158:161], v[4:5], off
	global_load_dwordx4 v[162:165], v[4:5], off offset:1024
	s_nop 0
	global_load_dwordx4 v[150:153], v[4:5], off offset:2048
	global_load_dwordx4 v[154:157], v[4:5], off offset:3072
	s_lshl_b64 s[0:1], s[44:45], 15
	s_add_u32 s0, s19, s0
	s_addc_u32 s1, s21, s1
	s_add_u32 s0, s0, s12
	s_addc_u32 s1, s1, s13
	s_waitcnt vmcnt(0)
	v_mul_f32_e32 v134, 0xbfb8aa3b, v134
	v_mul_f32_e32 v135, 0xbfb8aa3b, v135
	v_mul_f32_e32 v136, 0xbfb8aa3b, v136
	v_mul_f32_e32 v137, 0xbfb8aa3b, v137
	v_mul_f32_e32 v138, 0xbfb8aa3b, v138
	v_mul_f32_e32 v139, 0xbfb8aa3b, v139
	v_mul_f32_e32 v140, 0xbfb8aa3b, v140
	v_mul_f32_e32 v141, 0xbfb8aa3b, v141
	v_mul_f32_e32 v142, 0xbfb8aa3b, v142
	v_mul_f32_e32 v143, 0xbfb8aa3b, v143
	v_mul_f32_e32 v144, 0xbfb8aa3b, v144
	v_mul_f32_e32 v145, 0xbfb8aa3b, v145
	v_mul_f32_e32 v146, 0xbfb8aa3b, v146
	v_mul_f32_e32 v147, 0xbfb8aa3b, v147
	v_mul_f32_e32 v148, 0xbfb8aa3b, v148
	v_mul_f32_e32 v149, 0xbfb8aa3b, v149
	ds_write_b128 v3, v[228:231]
	ds_write_b128 v3, v[232:235] offset:1152
	ds_read_b128 v[228:231], v227
	ds_read_b128 v[232:235], v227 offset:64
	s_waitcnt lgkmcnt(1)
	v_lshlrev_b32_e32 v4, 16, v228
	v_lshlrev_b32_e32 v244, 16, v230
	v_fma_f32 v4, v4, s89, v146
	v_med3_f32 v4, v4, s85, v226
	v_fma_f32 v244, v244, s89, v142
	v_med3_f32 v244, v244, s85, v226
	v_exp_f32_e32 v4, v4
	v_exp_f32_e32 v244, v244
	v_and_b32_e32 v5, 0xffff0000, v228
	v_lshlrev_b32_e32 v228, 16, v229
	v_fma_f32 v228, v228, s89, v148
	v_and_b32_e32 v230, 0xffff0000, v230
	v_fma_f32 v5, v5, s89, v147
	v_fma_f32 v230, v230, s89, v143
	v_med3_f32 v228, v228, s85, v226
	v_add_f32_e32 v4, 1.0, v4
	v_add_f32_e32 v244, 1.0, v244
	v_exp_f32_e32 v228, v228
	v_rcp_f32_e32 v4, v4
	v_rcp_f32_e32 v244, v244
	v_med3_f32 v5, v5, s85, v226
	v_med3_f32 v230, v230, s85, v226
	v_exp_f32_e32 v5, v5
	v_exp_f32_e32 v230, v230
	v_and_b32_e32 v229, 0xffff0000, v229
	v_lshlrev_b32_e32 v245, 16, v231
	v_and_b32_e32 v231, 0xffff0000, v231
	v_fma_f32 v245, v245, s89, v144
	v_mul_f32_e32 v4, v130, v4
	v_mul_f32_e32 v130, v126, v244
	v_add_f32_e32 v126, 1.0, v228
	v_fma_f32 v228, v229, s89, v149
	v_fma_f32 v229, v231, s89, v145
	v_med3_f32 v245, v245, s85, v226
	v_add_f32_e32 v5, 1.0, v5
	v_add_f32_e32 v230, 1.0, v230
	v_med3_f32 v228, v228, s85, v226
	v_exp_f32_e32 v245, v245
	v_rcp_f32_e32 v5, v5
	v_rcp_f32_e32 v230, v230
	v_exp_f32_e32 v228, v228
	v_med3_f32 v229, v229, s85, v226
	v_exp_f32_e32 v229, v229
	v_mul_f32_e32 v5, v131, v5
	v_mul_f32_e32 v131, v127, v230
	v_add_f32_e32 v127, 1.0, v245
	v_add_f32_e32 v228, 1.0, v228
	v_rcp_f32_e32 v126, v126
	v_rcp_f32_e32 v127, v127
	v_rcp_f32_e32 v228, v228
	v_add_f32_e32 v229, 1.0, v229
	v_rcp_f32_e32 v229, v229
	v_mul_f32_e32 v132, v132, v126
	v_mul_f32_e32 v230, v128, v127
	v_mul_f32_e32 v127, v133, v228
	v_cvt_pk_bf16_f32 v126, v4, v5
	s_waitcnt lgkmcnt(0)
; __device__ __forceinline__ u32x4 pack8(const f32x4& v0, const f32x4& v1) { u32x4 w; w.x = cvt_pk_bf16(v0[0], v0[1]); w.y = cvt_pk_bf16(v0[2], v0[3]); w.z = cvt_pk_bf16(v1[0], v1[1]); w.w = cvt_pk_bf16(v1[2], v1[3]); return w; }
; #define UNPK0(q_) ((f32x4){bf_lo((q_).x), bf_hi((q_).x), bf_lo((q_).y), bf_hi((q_).y)})
; #define UNPK1(q_) ((f32x4){bf_lo((q_).z), bf_hi((q_).z), bf_lo((q_).w), bf_hi((q_).w)})
;     static __device__ __forceinline__ float eneg(float g) { return __builtin_amdgcn_exp2f(-1.4426950408889634f * fminf(fmaxf(g, -30.f), 30.f)); }
;     __device__ __forceinline__ void operator()(const f32x4 (&acc)[2][2][4][2], const Unit& u, int wr, int wc, int fr, int fq) const {
;     ...
;         for (int ai = 0; ai < 2; ++ai)
; #pragma unroll
;             for (int m = 0; m < 4; ++m) {
;                 pb.stage(rb[ai][m][0], rb[ai][m][1]); const u32x4 gb0 = pb.get(0), gb1 = pb.get(1);
;                 asm volatile("" ::: "memory");
; #pragma unroll
;                 for (int bj = 0; bj < 2; ++bj) { const u32x4 gb = bj ? gb1 : gb0;
;                     const f32x4 b0 = UNPK0(gb) + bb[bj][0], b1 = UNPK1(gb) + bb[bj][1];
;                     f32x4 v0 = acc[ai][bj][m][0], v1 = acc[ai][bj][m][1];
; #pragma unroll
;                     for (int k = 0; k < 4; ++k) { v0[k] *= __builtin_amdgcn_rcpf(1.0f + eneg(b0[k])); v1[k] *= __builtin_amdgcn_rcpf(1.0f + eneg(b1[k])); }
;                     po.put(bj, pack8(v0, v1)); }
;                 po.flush<false>(ai, m);
;                 asm volatile("" ::: "memory"); }
	v_and_b32_e32 v5, 0xffff0000, v232
	v_mul_f32_e32 v129, v129, v229
	v_cvt_pk_bf16_f32 v127, v132, v127
	v_cvt_pk_bf16_f32 v128, v130, v131
	v_fma_f32 v5, v5, s89, v139
	v_cvt_pk_bf16_f32 v129, v230, v129
	ds_write_b128 v227, v[126:129]
	v_lshlrev_b32_e32 v4, 16, v232
	v_lshlrev_b32_e32 v128, 16, v234
	v_fma_f32 v4, v4, s89, v138
	v_fma_f32 v128, v128, s89, v134
	v_med3_f32 v5, v5, s85, v226
	v_exp_f32_e32 v5, v5
	v_med3_f32 v4, v4, s85, v226
	v_med3_f32 v128, v128, s85, v226
	v_exp_f32_e32 v4, v4
	v_exp_f32_e32 v128, v128
	v_and_b32_e32 v129, 0xffff0000, v234
	v_add_f32_e32 v5, 1.0, v5
	v_fma_f32 v129, v129, s89, v135
	v_rcp_f32_e32 v5, v5
	v_add_f32_e32 v4, 1.0, v4
	v_add_f32_e32 v128, 1.0, v128
	v_med3_f32 v129, v129, s85, v226
	v_rcp_f32_e32 v4, v4
	v_rcp_f32_e32 v128, v128
	v_exp_f32_e32 v129, v129
	v_lshlrev_b32_e32 v126, 16, v233
	v_lshlrev_b32_e32 v130, 16, v235
	v_mul_f32_e32 v5, v123, v5
	v_fma_f32 v123, v126, s89, v140
	v_fma_f32 v126, v130, s89, v136
	v_mul_f32_e32 v4, v122, v4
	v_mul_f32_e32 v122, v118, v128
	v_add_f32_e32 v118, 1.0, v129
	v_med3_f32 v123, v123, s85, v226
	v_med3_f32 v126, v126, s85, v226
	v_rcp_f32_e32 v118, v118
	v_exp_f32_e32 v123, v123
	v_exp_f32_e32 v126, v126
	v_and_b32_e32 v127, 0xffff0000, v233
	v_and_b32_e32 v131, 0xffff0000, v235
	v_mul_f32_e32 v128, v119, v118
	v_add_f32_e32 v118, 1.0, v123
	v_add_f32_e32 v119, 1.0, v126
	v_fma_f32 v123, v127, s89, v141
	v_fma_f32 v126, v131, s89, v137
	v_med3_f32 v123, v123, s85, v226
	v_med3_f32 v126, v126, s85, v226
	v_exp_f32_e32 v123, v123
	v_exp_f32_e32 v126, v126
	v_rcp_f32_e32 v119, v119
	v_rcp_f32_e32 v118, v118
	v_add_f32_e32 v123, 1.0, v123
	v_add_f32_e32 v126, 1.0, v126
	v_rcp_f32_e32 v123, v123
	v_rcp_f32_e32 v126, v126
	v_mul_f32_e32 v127, v120, v119
	v_mul_f32_e32 v124, v124, v118
	v_mul_f32_e32 v119, v125, v123
	v_mul_f32_e32 v121, v121, v126
	v_cvt_pk_bf16_f32 v118, v4, v5
	v_cvt_pk_bf16_f32 v119, v124, v119
	v_cvt_pk_bf16_f32 v120, v122, v128
	v_cvt_pk_bf16_f32 v121, v127, v121
	ds_write_b128 v227, v[118:121] offset:64
	ds_read_b128 v[118:121], v3
	ds_read_b128 v[122:125], v3 offset:1152
	v_lshl_add_u64 v[4:5], s[0:1], 0, v[206:207]
	s_waitcnt lgkmcnt(1)
	global_store_dwordx4 v[4:5], v[118:121], off
	s_waitcnt lgkmcnt(0)
	global_store_dwordx4 v[4:5], v[122:125], off offset:1024
	ds_write_b128 v3, v[236:239]
	ds_write_b128 v3, v[240:243] offset:1152
	ds_read_b128 v[118:121], v227
	ds_read_b128 v[122:125], v227 offset:64
	s_waitcnt lgkmcnt(1)
	v_lshlrev_b32_e32 v126, 16, v118
	v_and_b32_e32 v118, 0xffff0000, v118
	v_lshlrev_b32_e32 v128, 16, v120
	v_fma_f32 v126, v126, s89, v146
	v_fma_f32 v128, v128, s89, v142
	v_fma_f32 v118, v118, s89, v147
	v_med3_f32 v126, v126, s85, v226
	v_med3_f32 v128, v128, s85, v226
	v_med3_f32 v118, v118, s85, v226
	v_exp_f32_e32 v126, v126
	v_exp_f32_e32 v128, v128
	v_exp_f32_e32 v118, v118
	v_and_b32_e32 v120, 0xffff0000, v120
	v_fma_f32 v120, v120, s89, v143
	v_add_f32_e32 v126, 1.0, v126
	v_add_f32_e32 v128, 1.0, v128
	v_add_f32_e32 v118, 1.0, v118
	v_med3_f32 v120, v120, s85, v226
	v_rcp_f32_e32 v126, v126
	v_rcp_f32_e32 v128, v128
	v_rcp_f32_e32 v118, v118
	v_exp_f32_e32 v120, v120
	v_lshlrev_b32_e32 v127, 16, v119
	v_lshlrev_b32_e32 v129, 16, v121
	v_mul_f32_e32 v114, v114, v126
	v_mul_f32_e32 v126, v110, v128
	v_mul_f32_e32 v110, v115, v118
	v_add_f32_e32 v115, 1.0, v120
	v_fma_f32 v118, v127, s89, v148
	v_fma_f32 v120, v129, s89, v144
	v_med3_f32 v118, v118, s85, v226
	v_med3_f32 v120, v120, s85, v226
	v_rcp_f32_e32 v115, v115
	v_exp_f32_e32 v118, v118
	v_exp_f32_e32 v120, v120
	v_and_b32_e32 v119, 0xffff0000, v119
	v_and_b32_e32 v121, 0xffff0000, v121
	v_mul_f32_e32 v115, v111, v115
	v_add_f32_e32 v111, 1.0, v118
	v_add_f32_e32 v118, 1.0, v120
	v_fma_f32 v119, v119, s89, v149
	v_fma_f32 v120, v121, s89, v145
	v_med3_f32 v119, v119, s85, v226
	v_med3_f32 v120, v120, s85, v226
	v_exp_f32_e32 v119, v119
	v_exp_f32_e32 v120, v120
	v_rcp_f32_e32 v111, v111
	v_rcp_f32_e32 v118, v118
	v_add_f32_e32 v119, 1.0, v119
	v_add_f32_e32 v120, 1.0, v120
	v_rcp_f32_e32 v119, v119
	v_rcp_f32_e32 v120, v120
	v_mul_f32_e32 v111, v116, v111
	v_mul_f32_e32 v116, v112, v118
	v_mul_f32_e32 v112, v117, v119
	v_mul_f32_e32 v113, v113, v120
	v_cvt_pk_bf16_f32 v110, v114, v110
	v_cvt_pk_bf16_f32 v111, v111, v112
	v_cvt_pk_bf16_f32 v112, v126, v115
	v_cvt_pk_bf16_f32 v113, v116, v113
	ds_write_b128 v227, v[110:113]
	s_waitcnt lgkmcnt(1)
	v_lshlrev_b32_e32 v110, 16, v122
	v_and_b32_e32 v111, 0xffff0000, v122
	v_lshlrev_b32_e32 v114, 16, v124
	v_fma_f32 v110, v110, s89, v138
	v_fma_f32 v114, v114, s89, v134
	v_fma_f32 v111, v111, s89, v139
	v_med3_f32 v110, v110, s85, v226
	v_med3_f32 v114, v114, s85, v226
	v_med3_f32 v111, v111, s85, v226
	v_exp_f32_e32 v110, v110
	v_exp_f32_e32 v114, v114
	v_exp_f32_e32 v111, v111
	v_and_b32_e32 v115, 0xffff0000, v124
	v_add_f32_e32 v110, 1.0, v110
	v_add_f32_e32 v114, 1.0, v114
	v_add_f32_e32 v111, 1.0, v111
	v_fma_f32 v115, v115, s89, v135
	v_rcp_f32_e32 v110, v110
	v_rcp_f32_e32 v114, v114
	v_rcp_f32_e32 v111, v111
	v_med3_f32 v115, v115, s85, v226
	v_exp_f32_e32 v115, v115
	v_lshlrev_b32_e32 v112, 16, v123
	v_lshlrev_b32_e32 v116, 16, v125
	v_mul_f32_e32 v106, v106, v110
	v_mul_f32_e32 v110, v102, v114
	v_mul_f32_e32 v102, v107, v111
	v_fma_f32 v111, v112, s89, v140
	v_fma_f32 v112, v116, s89, v136
	v_add_f32_e32 v107, 1.0, v115
	v_med3_f32 v111, v111, s85, v226
	v_med3_f32 v112, v112, s85, v226
	v_rcp_f32_e32 v107, v107
	v_exp_f32_e32 v111, v111
	v_exp_f32_e32 v112, v112
	v_and_b32_e32 v113, 0xffff0000, v123
	v_and_b32_e32 v117, 0xffff0000, v125
	v_mul_f32_e32 v107, v103, v107
	v_add_f32_e32 v103, 1.0, v111
	v_add_f32_e32 v111, 1.0, v112
	v_fma_f32 v112, v113, s89, v141
	v_fma_f32 v113, v117, s89, v137
	v_med3_f32 v112, v112, s85, v226
	v_med3_f32 v113, v113, s85, v226
	v_exp_f32_e32 v112, v112
	v_exp_f32_e32 v113, v113
	v_rcp_f32_e32 v103, v103
	v_rcp_f32_e32 v111, v111
	v_add_f32_e32 v112, 1.0, v112
	v_add_f32_e32 v113, 1.0, v113
	v_rcp_f32_e32 v112, v112
	v_rcp_f32_e32 v113, v113
	v_mul_f32_e32 v103, v108, v103
	v_mul_f32_e32 v108, v104, v111
	v_mul_f32_e32 v104, v109, v112
	v_mul_f32_e32 v105, v105, v113
	v_cvt_pk_bf16_f32 v102, v106, v102
	v_cvt_pk_bf16_f32 v103, v103, v104
	v_cvt_pk_bf16_f32 v104, v110, v107
	v_cvt_pk_bf16_f32 v105, v108, v105
	ds_write_b128 v227, v[102:105] offset:64
	ds_read_b128 v[102:105], v3
	ds_read_b128 v[106:109], v3 offset:1152
	s_waitcnt lgkmcnt(1)
; __device__ __forceinline__ u32x4 pack8(const f32x4& v0, const f32x4& v1) { u32x4 w; w.x = cvt_pk_bf16(v0[0], v0[1]); w.y = cvt_pk_bf16(v0[2], v0[3]); w.z = cvt_pk_bf16(v1[0], v1[1]); w.w = cvt_pk_bf16(v1[2], v1[3]); return w; }
; #define UNPK0(q_) ((f32x4){bf_lo((q_).x), bf_hi((q_).x), bf_lo((q_).y), bf_hi((q_).y)})
; #define UNPK1(q_) ((f32x4){bf_lo((q_).z), bf_hi((q_).z), bf_lo((q_).w), bf_hi((q_).w)})
;     static __device__ __forceinline__ float eneg(float g) { return __builtin_amdgcn_exp2f(-1.4426950408889634f * fminf(fmaxf(g, -30.f), 30.f)); }
;     __device__ __forceinline__ void operator()(const f32x4 (&acc)[2][2][4][2], const Unit& u, int wr, int wc, int fr, int fq) const {
;     ...
;         for (int ai = 0; ai < 2; ++ai)
; #pragma unroll
;             for (int m = 0; m < 4; ++m) {
;                 pb.stage(rb[ai][m][0], rb[ai][m][1]); const u32x4 gb0 = pb.get(0), gb1 = pb.get(1);
;                 asm volatile("" ::: "memory");
; #pragma unroll
;                 for (int bj = 0; bj < 2; ++bj) { const u32x4 gb = bj ? gb1 : gb0;
;                     const f32x4 b0 = UNPK0(gb) + bb[bj][0], b1 = UNPK1(gb) + bb[bj][1];
;                     f32x4 v0 = acc[ai][bj][m][0], v1 = acc[ai][bj][m][1];
; #pragma unroll
;                     for (int k = 0; k < 4; ++k) { v0[k] *= __builtin_amdgcn_rcpf(1.0f + eneg(b0[k])); v1[k] *= __builtin_amdgcn_rcpf(1.0f + eneg(b1[k])); }
;                     po.put(bj, pack8(v0, v1)); }
;                 po.flush<false>(ai, m);
;                 asm volatile("" ::: "memory"); }
	global_store_dwordx4 v[4:5], v[102:105], off offset:2048
	s_waitcnt lgkmcnt(0)
	global_store_dwordx4 v[4:5], v[106:109], off offset:3072
	ds_write_b128 v3, v[190:193]
	ds_write_b128 v3, v[194:197] offset:1152
	ds_read_b128 v[102:105], v227
	ds_read_b128 v[106:109], v227 offset:64
	s_waitcnt lgkmcnt(1)
	v_lshlrev_b32_e32 v110, 16, v102
	v_and_b32_e32 v102, 0xffff0000, v102
	v_lshlrev_b32_e32 v112, 16, v104
	v_fma_f32 v110, v110, s89, v146
	v_fma_f32 v112, v112, s89, v142
	v_fma_f32 v102, v102, s89, v147
	v_med3_f32 v110, v110, s85, v226
	v_med3_f32 v112, v112, s85, v226
	v_med3_f32 v102, v102, s85, v226
	v_exp_f32_e32 v110, v110
	v_exp_f32_e32 v112, v112
	v_exp_f32_e32 v102, v102
	v_and_b32_e32 v104, 0xffff0000, v104
	v_fma_f32 v104, v104, s89, v143
	v_add_f32_e32 v110, 1.0, v110
	v_add_f32_e32 v112, 1.0, v112
	v_add_f32_e32 v102, 1.0, v102
	v_med3_f32 v104, v104, s85, v226
	v_rcp_f32_e32 v110, v110
	v_rcp_f32_e32 v112, v112
	v_rcp_f32_e32 v102, v102
	v_exp_f32_e32 v104, v104
	v_lshlrev_b32_e32 v111, 16, v103
	v_lshlrev_b32_e32 v113, 16, v105
	v_mul_f32_e32 v98, v98, v110
	v_mul_f32_e32 v110, v94, v112
	v_mul_f32_e32 v94, v99, v102
	v_add_f32_e32 v99, 1.0, v104
	v_fma_f32 v102, v111, s89, v148
	v_fma_f32 v104, v113, s89, v144
	v_med3_f32 v102, v102, s85, v226
	v_med3_f32 v104, v104, s85, v226
	v_rcp_f32_e32 v99, v99
	v_exp_f32_e32 v102, v102
	v_exp_f32_e32 v104, v104
	v_and_b32_e32 v103, 0xffff0000, v103
	v_and_b32_e32 v105, 0xffff0000, v105
	v_mul_f32_e32 v99, v95, v99
	v_add_f32_e32 v95, 1.0, v102
	v_add_f32_e32 v102, 1.0, v104
	v_fma_f32 v103, v103, s89, v149
	v_fma_f32 v104, v105, s89, v145
	v_med3_f32 v103, v103, s85, v226
	v_med3_f32 v104, v104, s85, v226
	v_exp_f32_e32 v103, v103
	v_exp_f32_e32 v104, v104
	v_rcp_f32_e32 v95, v95
	v_rcp_f32_e32 v102, v102
	v_add_f32_e32 v103, 1.0, v103
	v_add_f32_e32 v104, 1.0, v104
	v_rcp_f32_e32 v103, v103
	v_rcp_f32_e32 v104, v104
	v_mul_f32_e32 v95, v100, v95
	v_mul_f32_e32 v100, v96, v102
	v_mul_f32_e32 v96, v101, v103
	v_mul_f32_e32 v97, v97, v104
	v_cvt_pk_bf16_f32 v94, v98, v94
	v_cvt_pk_bf16_f32 v95, v95, v96
	v_cvt_pk_bf16_f32 v96, v110, v99
	v_cvt_pk_bf16_f32 v97, v100, v97
	ds_write_b128 v227, v[94:97]
	s_waitcnt lgkmcnt(1)
	v_lshlrev_b32_e32 v94, 16, v106
	v_and_b32_e32 v95, 0xffff0000, v106
	v_lshlrev_b32_e32 v98, 16, v108
	v_fma_f32 v94, v94, s89, v138
	v_fma_f32 v98, v98, s89, v134
	v_fma_f32 v95, v95, s89, v139
	v_med3_f32 v94, v94, s85, v226
	v_med3_f32 v98, v98, s85, v226
	v_med3_f32 v95, v95, s85, v226
	v_exp_f32_e32 v94, v94
	v_exp_f32_e32 v98, v98
	v_exp_f32_e32 v95, v95
	v_and_b32_e32 v99, 0xffff0000, v108
	v_add_f32_e32 v94, 1.0, v94
	v_add_f32_e32 v98, 1.0, v98
	v_add_f32_e32 v95, 1.0, v95
	v_fma_f32 v99, v99, s89, v135
	v_rcp_f32_e32 v94, v94
	v_rcp_f32_e32 v98, v98
	v_rcp_f32_e32 v95, v95
	v_med3_f32 v99, v99, s85, v226
	v_exp_f32_e32 v99, v99
	v_lshlrev_b32_e32 v96, 16, v107
	v_lshlrev_b32_e32 v100, 16, v109
	v_mul_f32_e32 v90, v90, v94
	v_mul_f32_e32 v94, v86, v98
	v_mul_f32_e32 v86, v91, v95
	v_fma_f32 v95, v96, s89, v140
	v_fma_f32 v96, v100, s89, v136
	v_add_f32_e32 v91, 1.0, v99
	v_med3_f32 v95, v95, s85, v226
	v_med3_f32 v96, v96, s85, v226
	v_rcp_f32_e32 v91, v91
	v_exp_f32_e32 v95, v95
	v_exp_f32_e32 v96, v96
	v_and_b32_e32 v97, 0xffff0000, v107
	v_and_b32_e32 v101, 0xffff0000, v109
	v_mul_f32_e32 v91, v87, v91
	v_add_f32_e32 v87, 1.0, v95
	v_add_f32_e32 v95, 1.0, v96
	v_fma_f32 v96, v97, s89, v141
	v_fma_f32 v97, v101, s89, v137
	v_med3_f32 v96, v96, s85, v226
	v_med3_f32 v97, v97, s85, v226
	v_exp_f32_e32 v96, v96
	v_exp_f32_e32 v97, v97
	v_rcp_f32_e32 v87, v87
	v_rcp_f32_e32 v95, v95
	v_add_f32_e32 v96, 1.0, v96
	v_add_f32_e32 v97, 1.0, v97
	v_rcp_f32_e32 v96, v96
	v_rcp_f32_e32 v97, v97
	v_mul_f32_e32 v87, v92, v87
	v_mul_f32_e32 v92, v88, v95
	v_mul_f32_e32 v88, v93, v96
	v_mul_f32_e32 v89, v89, v97
	v_cvt_pk_bf16_f32 v86, v90, v86
	v_cvt_pk_bf16_f32 v87, v87, v88
	v_cvt_pk_bf16_f32 v88, v94, v91
	v_cvt_pk_bf16_f32 v89, v92, v89
	ds_write_b128 v227, v[86:89] offset:64
	ds_read_b128 v[86:89], v3
	ds_read_b128 v[90:93], v3 offset:1152
	v_add_co_u32_e32 v94, vcc, s84, v4
	s_nop 1
	v_addc_co_u32_e32 v95, vcc, 0, v5, vcc
	s_waitcnt lgkmcnt(1)
	global_store_dwordx4 v[94:95], v[86:89], off
	s_waitcnt lgkmcnt(0)
	global_store_dwordx4 v[94:95], v[90:93], off offset:1024
	ds_write_b128 v3, v[182:185]
	ds_write_b128 v3, v[186:189] offset:1152
	ds_read_b128 v[86:89], v227
	ds_read_b128 v[90:93], v227 offset:64
	s_waitcnt lgkmcnt(1)
	v_lshlrev_b32_e32 v96, 16, v86
	v_and_b32_e32 v86, 0xffff0000, v86
	v_lshlrev_b32_e32 v98, 16, v88
	v_fma_f32 v96, v96, s89, v146
	v_fma_f32 v98, v98, s89, v142
	v_fma_f32 v86, v86, s89, v147
	v_med3_f32 v96, v96, s85, v226
	v_med3_f32 v98, v98, s85, v226
	v_med3_f32 v86, v86, s85, v226
	v_exp_f32_e32 v96, v96
	v_exp_f32_e32 v98, v98
	v_exp_f32_e32 v86, v86
	v_and_b32_e32 v88, 0xffff0000, v88
	v_fma_f32 v88, v88, s89, v143
	v_add_f32_e32 v96, 1.0, v96
	v_add_f32_e32 v98, 1.0, v98
	v_add_f32_e32 v86, 1.0, v86
	v_med3_f32 v88, v88, s85, v226
	v_rcp_f32_e32 v96, v96
	v_rcp_f32_e32 v98, v98
	v_rcp_f32_e32 v86, v86
	v_exp_f32_e32 v88, v88
	v_lshlrev_b32_e32 v97, 16, v87
	v_lshlrev_b32_e32 v99, 16, v89
	v_mul_f32_e32 v82, v82, v96
	v_mul_f32_e32 v96, v78, v98
	v_mul_f32_e32 v78, v83, v86
	v_add_f32_e32 v83, 1.0, v88
	v_fma_f32 v86, v97, s89, v148
	v_fma_f32 v88, v99, s89, v144
	v_med3_f32 v86, v86, s85, v226
	v_med3_f32 v88, v88, s85, v226
	v_rcp_f32_e32 v83, v83
	v_exp_f32_e32 v86, v86
	v_exp_f32_e32 v88, v88
	v_and_b32_e32 v87, 0xffff0000, v87
	v_and_b32_e32 v89, 0xffff0000, v89
	v_mul_f32_e32 v83, v79, v83
	v_add_f32_e32 v79, 1.0, v86
	v_add_f32_e32 v86, 1.0, v88
	v_fma_f32 v87, v87, s89, v149
	v_fma_f32 v88, v89, s89, v145
	v_med3_f32 v87, v87, s85, v226
	v_med3_f32 v88, v88, s85, v226
	v_exp_f32_e32 v87, v87
	v_exp_f32_e32 v88, v88
	v_rcp_f32_e32 v79, v79
	v_rcp_f32_e32 v86, v86
	v_add_f32_e32 v87, 1.0, v87
	v_add_f32_e32 v88, 1.0, v88
	v_rcp_f32_e32 v87, v87
	v_rcp_f32_e32 v88, v88
	v_mul_f32_e32 v79, v84, v79
	v_mul_f32_e32 v84, v80, v86
	v_mul_f32_e32 v80, v85, v87
	v_mul_f32_e32 v81, v81, v88
	v_cvt_pk_bf16_f32 v78, v82, v78
	v_cvt_pk_bf16_f32 v79, v79, v80
	v_cvt_pk_bf16_f32 v80, v96, v83
	v_cvt_pk_bf16_f32 v81, v84, v81
	ds_write_b128 v227, v[78:81]
	s_waitcnt lgkmcnt(1)
; __device__ __forceinline__ u32x4 pack8(const f32x4& v0, const f32x4& v1) { u32x4 w; w.x = cvt_pk_bf16(v0[0], v0[1]); w.y = cvt_pk_bf16(v0[2], v0[3]); w.z = cvt_pk_bf16(v1[0], v1[1]); w.w = cvt_pk_bf16(v1[2], v1[3]); return w; }
; #define UNPK0(q_) ((f32x4){bf_lo((q_).x), bf_hi((q_).x), bf_lo((q_).y), bf_hi((q_).y)})
; #define UNPK1(q_) ((f32x4){bf_lo((q_).z), bf_hi((q_).z), bf_lo((q_).w), bf_hi((q_).w)})
;     static __device__ __forceinline__ float eneg(float g) { return __builtin_amdgcn_exp2f(-1.4426950408889634f * fminf(fmaxf(g, -30.f), 30.f)); }
;     __device__ __forceinline__ void operator()(const f32x4 (&acc)[2][2][4][2], const Unit& u, int wr, int wc, int fr, int fq) const {
;     ...
;         for (int ai = 0; ai < 2; ++ai)
; #pragma unroll
;             for (int m = 0; m < 4; ++m) {
;                 pb.stage(rb[ai][m][0], rb[ai][m][1]); const u32x4 gb0 = pb.get(0), gb1 = pb.get(1);
;                 asm volatile("" ::: "memory");
; #pragma unroll
;                 for (int bj = 0; bj < 2; ++bj) { const u32x4 gb = bj ? gb1 : gb0;
;                     const f32x4 b0 = UNPK0(gb) + bb[bj][0], b1 = UNPK1(gb) + bb[bj][1];
;                     f32x4 v0 = acc[ai][bj][m][0], v1 = acc[ai][bj][m][1];
; #pragma unroll
;                     for (int k = 0; k < 4; ++k) { v0[k] *= __builtin_amdgcn_rcpf(1.0f + eneg(b0[k])); v1[k] *= __builtin_amdgcn_rcpf(1.0f + eneg(b1[k])); }
;                     po.put(bj, pack8(v0, v1)); }
;                 po.flush<false>(ai, m);
;                 asm volatile("" ::: "memory"); }
	v_lshlrev_b32_e32 v78, 16, v90
	v_and_b32_e32 v79, 0xffff0000, v90
	v_lshlrev_b32_e32 v82, 16, v92
	v_fma_f32 v78, v78, s89, v138
	v_fma_f32 v82, v82, s89, v134
	v_fma_f32 v79, v79, s89, v139
	v_med3_f32 v78, v78, s85, v226
	v_med3_f32 v82, v82, s85, v226
	v_med3_f32 v79, v79, s85, v226
	v_exp_f32_e32 v78, v78
	v_exp_f32_e32 v82, v82
	v_exp_f32_e32 v79, v79
	v_and_b32_e32 v83, 0xffff0000, v92
	v_add_f32_e32 v78, 1.0, v78
	v_add_f32_e32 v82, 1.0, v82
	v_add_f32_e32 v79, 1.0, v79
	v_fma_f32 v83, v83, s89, v135
	v_rcp_f32_e32 v78, v78
	v_rcp_f32_e32 v82, v82
	v_rcp_f32_e32 v79, v79
	v_med3_f32 v83, v83, s85, v226
	v_exp_f32_e32 v83, v83
	v_lshlrev_b32_e32 v80, 16, v91
	v_lshlrev_b32_e32 v84, 16, v93
	v_mul_f32_e32 v74, v74, v78
	v_mul_f32_e32 v78, v70, v82
	v_mul_f32_e32 v70, v75, v79
	v_fma_f32 v79, v80, s89, v140
	v_fma_f32 v80, v84, s89, v136
	v_add_f32_e32 v75, 1.0, v83
	v_med3_f32 v79, v79, s85, v226
	v_med3_f32 v80, v80, s85, v226
	v_rcp_f32_e32 v75, v75
	v_exp_f32_e32 v79, v79
	v_exp_f32_e32 v80, v80
	v_and_b32_e32 v81, 0xffff0000, v91
	v_and_b32_e32 v85, 0xffff0000, v93
	v_mul_f32_e32 v75, v71, v75
	v_add_f32_e32 v71, 1.0, v79
	v_add_f32_e32 v79, 1.0, v80
	v_fma_f32 v80, v81, s89, v141
	v_fma_f32 v81, v85, s89, v137
	v_med3_f32 v80, v80, s85, v226
	v_med3_f32 v81, v81, s85, v226
	v_exp_f32_e32 v80, v80
	v_exp_f32_e32 v81, v81
	v_rcp_f32_e32 v71, v71
	v_rcp_f32_e32 v79, v79
	v_add_f32_e32 v80, 1.0, v80
	v_add_f32_e32 v81, 1.0, v81
	v_rcp_f32_e32 v80, v80
	v_rcp_f32_e32 v81, v81
	v_mul_f32_e32 v71, v76, v71
	v_mul_f32_e32 v76, v72, v79
	v_mul_f32_e32 v72, v77, v80
	v_mul_f32_e32 v73, v73, v81
	v_cvt_pk_bf16_f32 v70, v74, v70
	v_cvt_pk_bf16_f32 v71, v71, v72
	v_cvt_pk_bf16_f32 v72, v78, v75
	v_cvt_pk_bf16_f32 v73, v76, v73
	ds_write_b128 v227, v[70:73] offset:64
	ds_read_b128 v[70:73], v3
	ds_read_b128 v[74:77], v3 offset:1152
	s_waitcnt lgkmcnt(1)
	global_store_dwordx4 v[94:95], v[70:73], off offset:2048
	s_waitcnt lgkmcnt(0)
	global_store_dwordx4 v[94:95], v[74:77], off offset:3072
	ds_write_b128 v3, v[178:181]
	ds_write_b128 v3, v[174:177] offset:1152
	ds_read_b128 v[70:73], v227
	ds_read_b128 v[74:77], v227 offset:64
	s_waitcnt lgkmcnt(1)
	v_lshlrev_b32_e32 v78, 16, v70
	v_and_b32_e32 v70, 0xffff0000, v70
	v_lshlrev_b32_e32 v80, 16, v72
	v_fma_f32 v78, v78, s89, v146
	v_fma_f32 v80, v80, s89, v142
	v_fma_f32 v70, v70, s89, v147
	v_med3_f32 v78, v78, s85, v226
	v_med3_f32 v80, v80, s85, v226
	v_med3_f32 v70, v70, s85, v226
	v_exp_f32_e32 v78, v78
	v_exp_f32_e32 v80, v80
	v_exp_f32_e32 v70, v70
	v_and_b32_e32 v72, 0xffff0000, v72
	v_fma_f32 v72, v72, s89, v143
	v_add_f32_e32 v78, 1.0, v78
	v_add_f32_e32 v80, 1.0, v80
	v_add_f32_e32 v70, 1.0, v70
	v_med3_f32 v72, v72, s85, v226
	v_rcp_f32_e32 v78, v78
	v_rcp_f32_e32 v80, v80
	v_rcp_f32_e32 v70, v70
	v_exp_f32_e32 v72, v72
	v_lshlrev_b32_e32 v79, 16, v71
	v_lshlrev_b32_e32 v81, 16, v73
	v_mul_f32_e32 v66, v66, v78
	v_mul_f32_e32 v78, v62, v80
	v_mul_f32_e32 v62, v67, v70
	v_add_f32_e32 v67, 1.0, v72
	v_fma_f32 v70, v79, s89, v148
	v_fma_f32 v72, v81, s89, v144
	v_med3_f32 v70, v70, s85, v226
	v_med3_f32 v72, v72, s85, v226
	v_rcp_f32_e32 v67, v67
	v_exp_f32_e32 v70, v70
	v_exp_f32_e32 v72, v72
	v_and_b32_e32 v71, 0xffff0000, v71
	v_and_b32_e32 v73, 0xffff0000, v73
	v_mul_f32_e32 v67, v63, v67
	v_add_f32_e32 v63, 1.0, v70
	v_add_f32_e32 v70, 1.0, v72
	v_fma_f32 v71, v71, s89, v149
	v_fma_f32 v72, v73, s89, v145
	v_med3_f32 v71, v71, s85, v226
	v_med3_f32 v72, v72, s85, v226
	v_exp_f32_e32 v71, v71
	v_exp_f32_e32 v72, v72
	v_rcp_f32_e32 v63, v63
	v_rcp_f32_e32 v70, v70
	v_add_f32_e32 v71, 1.0, v71
	v_add_f32_e32 v72, 1.0, v72
	v_rcp_f32_e32 v71, v71
	v_rcp_f32_e32 v72, v72
	v_mul_f32_e32 v63, v68, v63
	v_mul_f32_e32 v68, v64, v70
	v_mul_f32_e32 v64, v69, v71
	v_mul_f32_e32 v65, v65, v72
	v_cvt_pk_bf16_f32 v62, v66, v62
	v_cvt_pk_bf16_f32 v63, v63, v64
	v_cvt_pk_bf16_f32 v64, v78, v67
	v_cvt_pk_bf16_f32 v65, v68, v65
	ds_write_b128 v227, v[62:65]
	s_waitcnt lgkmcnt(1)
	v_lshlrev_b32_e32 v62, 16, v74
	v_and_b32_e32 v63, 0xffff0000, v74
	v_lshlrev_b32_e32 v66, 16, v76
	v_fma_f32 v62, v62, s89, v138
	v_fma_f32 v66, v66, s89, v134
	v_fma_f32 v63, v63, s89, v139
	v_med3_f32 v62, v62, s85, v226
	v_med3_f32 v66, v66, s85, v226
	v_med3_f32 v63, v63, s85, v226
	v_exp_f32_e32 v62, v62
	v_exp_f32_e32 v66, v66
	v_exp_f32_e32 v63, v63
	v_and_b32_e32 v67, 0xffff0000, v76
	v_add_f32_e32 v62, 1.0, v62
	v_add_f32_e32 v66, 1.0, v66
	v_add_f32_e32 v63, 1.0, v63
	v_fma_f32 v67, v67, s89, v135
	v_rcp_f32_e32 v62, v62
	v_rcp_f32_e32 v66, v66
	v_rcp_f32_e32 v63, v63
	v_med3_f32 v67, v67, s85, v226
	v_exp_f32_e32 v67, v67
	v_lshlrev_b32_e32 v64, 16, v75
	v_lshlrev_b32_e32 v68, 16, v77
	v_mul_f32_e32 v58, v58, v62
	v_mul_f32_e32 v62, v54, v66
	v_mul_f32_e32 v54, v59, v63
	v_fma_f32 v63, v64, s89, v140
	v_fma_f32 v64, v68, s89, v136
	v_add_f32_e32 v59, 1.0, v67
	v_med3_f32 v63, v63, s85, v226
	v_med3_f32 v64, v64, s85, v226
	v_rcp_f32_e32 v59, v59
	v_exp_f32_e32 v63, v63
	v_exp_f32_e32 v64, v64
	v_and_b32_e32 v65, 0xffff0000, v75
	v_and_b32_e32 v69, 0xffff0000, v77
	v_mul_f32_e32 v59, v55, v59
	v_add_f32_e32 v55, 1.0, v63
	v_add_f32_e32 v63, 1.0, v64
	v_fma_f32 v64, v65, s89, v141
	v_fma_f32 v65, v69, s89, v137
	v_med3_f32 v64, v64, s85, v226
	v_med3_f32 v65, v65, s85, v226
	v_exp_f32_e32 v64, v64
	v_exp_f32_e32 v65, v65
	v_rcp_f32_e32 v55, v55
	v_rcp_f32_e32 v63, v63
	v_add_f32_e32 v64, 1.0, v64
	v_add_f32_e32 v65, 1.0, v65
	v_rcp_f32_e32 v64, v64
	v_rcp_f32_e32 v65, v65
	v_mul_f32_e32 v55, v60, v55
	v_mul_f32_e32 v60, v56, v63
	v_mul_f32_e32 v56, v61, v64
	v_mul_f32_e32 v57, v57, v65
	v_cvt_pk_bf16_f32 v54, v58, v54
	v_cvt_pk_bf16_f32 v55, v55, v56
	v_cvt_pk_bf16_f32 v56, v62, v59
	v_cvt_pk_bf16_f32 v57, v60, v57
	ds_write_b128 v227, v[54:57] offset:64
	ds_read_b128 v[54:57], v3
	ds_read_b128 v[58:61], v3 offset:1152
	v_add_co_u32_e32 v62, vcc, s79, v4
	s_nop 1
	v_addc_co_u32_e32 v63, vcc, 0, v5, vcc
	v_add_co_u32_e32 v4, vcc, s86, v4
	s_nop 1
	v_addc_co_u32_e32 v5, vcc, 0, v5, vcc
	s_waitcnt lgkmcnt(1)
; __device__ __forceinline__ u32x4 pack8(const f32x4& v0, const f32x4& v1) { u32x4 w; w.x = cvt_pk_bf16(v0[0], v0[1]); w.y = cvt_pk_bf16(v0[2], v0[3]); w.z = cvt_pk_bf16(v1[0], v1[1]); w.w = cvt_pk_bf16(v1[2], v1[3]); return w; }
; #define UNPK0(q_) ((f32x4){bf_lo((q_).x), bf_hi((q_).x), bf_lo((q_).y), bf_hi((q_).y)})
; #define UNPK1(q_) ((f32x4){bf_lo((q_).z), bf_hi((q_).z), bf_lo((q_).w), bf_hi((q_).w)})
;     static __device__ __forceinline__ float eneg(float g) { return __builtin_amdgcn_exp2f(-1.4426950408889634f * fminf(fmaxf(g, -30.f), 30.f)); }
;     __device__ __forceinline__ void operator()(const f32x4 (&acc)[2][2][4][2], const Unit& u, int wr, int wc, int fr, int fq) const {
;     ...
;         for (int ai = 0; ai < 2; ++ai)
; #pragma unroll
;             for (int m = 0; m < 4; ++m) {
;                 pb.stage(rb[ai][m][0], rb[ai][m][1]); const u32x4 gb0 = pb.get(0), gb1 = pb.get(1);
;                 asm volatile("" ::: "memory");
; #pragma unroll
;                 for (int bj = 0; bj < 2; ++bj) { const u32x4 gb = bj ? gb1 : gb0;
;                     const f32x4 b0 = UNPK0(gb) + bb[bj][0], b1 = UNPK1(gb) + bb[bj][1];
;                     f32x4 v0 = acc[ai][bj][m][0], v1 = acc[ai][bj][m][1];
; #pragma unroll
;                     for (int k = 0; k < 4; ++k) { v0[k] *= __builtin_amdgcn_rcpf(1.0f + eneg(b0[k])); v1[k] *= __builtin_amdgcn_rcpf(1.0f + eneg(b1[k])); }
;                     po.put(bj, pack8(v0, v1)); }
;                 po.flush<false>(ai, m);
;                 asm volatile("" ::: "memory"); }
	global_store_dwordx4 v[4:5], v[54:57], off offset:-4096
	s_waitcnt lgkmcnt(0)
	global_store_dwordx4 v[62:63], v[58:61], off offset:1024
	ds_write_b128 v3, v[166:169]
	ds_write_b128 v3, v[170:173] offset:1152
	ds_read_b128 v[54:57], v227
	ds_read_b128 v[58:61], v227 offset:64
	s_andn2_b64 vcc, exec, s[4:5]
	s_mov_b64 s[4:5], -1
	s_waitcnt lgkmcnt(1)
	v_lshlrev_b32_e32 v64, 16, v54
	v_and_b32_e32 v54, 0xffff0000, v54
	v_lshlrev_b32_e32 v66, 16, v56
	v_fma_f32 v64, v64, s89, v146
	v_fma_f32 v66, v66, s89, v142
	v_fma_f32 v54, v54, s89, v147
	v_med3_f32 v64, v64, s85, v226
	v_med3_f32 v66, v66, s85, v226
	v_med3_f32 v54, v54, s85, v226
	v_exp_f32_e32 v64, v64
	v_exp_f32_e32 v66, v66
	v_exp_f32_e32 v54, v54
	v_and_b32_e32 v56, 0xffff0000, v56
	v_fma_f32 v56, v56, s89, v143
	v_add_f32_e32 v64, 1.0, v64
	v_add_f32_e32 v66, 1.0, v66
	v_add_f32_e32 v54, 1.0, v54
	v_med3_f32 v56, v56, s85, v226
	v_rcp_f32_e32 v64, v64
	v_rcp_f32_e32 v66, v66
	v_rcp_f32_e32 v54, v54
	v_exp_f32_e32 v56, v56
	v_lshlrev_b32_e32 v65, 16, v55
	v_lshlrev_b32_e32 v67, 16, v57
	v_mul_f32_e32 v50, v50, v64
	v_mul_f32_e32 v64, v46, v66
	v_mul_f32_e32 v46, v51, v54
	v_add_f32_e32 v51, 1.0, v56
	v_fma_f32 v54, v65, s89, v148
	v_fma_f32 v56, v67, s89, v144
	v_med3_f32 v54, v54, s85, v226
	v_med3_f32 v56, v56, s85, v226
	v_rcp_f32_e32 v51, v51
	v_exp_f32_e32 v54, v54
	v_exp_f32_e32 v56, v56
	v_and_b32_e32 v55, 0xffff0000, v55
	v_and_b32_e32 v57, 0xffff0000, v57
	v_mul_f32_e32 v51, v47, v51
	v_add_f32_e32 v47, 1.0, v54
	v_add_f32_e32 v54, 1.0, v56
	v_fma_f32 v55, v55, s89, v149
	v_fma_f32 v56, v57, s89, v145
	v_med3_f32 v55, v55, s85, v226
	v_med3_f32 v56, v56, s85, v226
	v_exp_f32_e32 v55, v55
	v_exp_f32_e32 v56, v56
	v_rcp_f32_e32 v47, v47
	v_rcp_f32_e32 v54, v54
	v_add_f32_e32 v55, 1.0, v55
	v_add_f32_e32 v56, 1.0, v56
	v_rcp_f32_e32 v55, v55
	v_rcp_f32_e32 v56, v56
	v_mul_f32_e32 v47, v52, v47
	v_mul_f32_e32 v52, v48, v54
	v_mul_f32_e32 v48, v53, v55
	v_mul_f32_e32 v49, v49, v56
	v_cvt_pk_bf16_f32 v46, v50, v46
	v_cvt_pk_bf16_f32 v47, v47, v48
	v_cvt_pk_bf16_f32 v48, v64, v51
	v_cvt_pk_bf16_f32 v49, v52, v49
	ds_write_b128 v227, v[46:49]
	s_waitcnt lgkmcnt(1)
	v_lshlrev_b32_e32 v46, 16, v58
	v_and_b32_e32 v47, 0xffff0000, v58
	v_lshlrev_b32_e32 v50, 16, v60
	v_fma_f32 v46, v46, s89, v138
	v_fma_f32 v50, v50, s89, v134
	v_fma_f32 v47, v47, s89, v139
	v_med3_f32 v46, v46, s85, v226
	v_med3_f32 v50, v50, s85, v226
	v_med3_f32 v47, v47, s85, v226
	v_exp_f32_e32 v46, v46
	v_exp_f32_e32 v50, v50
	v_exp_f32_e32 v47, v47
	v_and_b32_e32 v51, 0xffff0000, v60
	v_add_f32_e32 v46, 1.0, v46
	v_add_f32_e32 v50, 1.0, v50
	v_add_f32_e32 v47, 1.0, v47
	v_fma_f32 v51, v51, s89, v135
	v_rcp_f32_e32 v46, v46
	v_rcp_f32_e32 v50, v50
	v_rcp_f32_e32 v47, v47
	v_med3_f32 v51, v51, s85, v226
	v_exp_f32_e32 v51, v51
	v_lshlrev_b32_e32 v48, 16, v59
	v_lshlrev_b32_e32 v52, 16, v61
	v_mul_f32_e32 v42, v42, v46
	v_mul_f32_e32 v46, v38, v50
	v_mul_f32_e32 v38, v43, v47
	v_fma_f32 v47, v48, s89, v140
	v_fma_f32 v48, v52, s89, v136
	v_add_f32_e32 v43, 1.0, v51
	v_med3_f32 v47, v47, s85, v226
	v_med3_f32 v48, v48, s85, v226
	v_rcp_f32_e32 v43, v43
	v_exp_f32_e32 v47, v47
	v_exp_f32_e32 v48, v48
	v_and_b32_e32 v49, 0xffff0000, v59
	v_and_b32_e32 v53, 0xffff0000, v61
	v_mul_f32_e32 v43, v39, v43
	v_add_f32_e32 v39, 1.0, v47
	v_add_f32_e32 v47, 1.0, v48
	v_fma_f32 v48, v49, s89, v141
	v_fma_f32 v49, v53, s89, v137
	v_med3_f32 v48, v48, s85, v226
	v_med3_f32 v49, v49, s85, v226
	v_exp_f32_e32 v48, v48
	v_exp_f32_e32 v49, v49
	v_rcp_f32_e32 v39, v39
	v_rcp_f32_e32 v47, v47
	v_add_f32_e32 v48, 1.0, v48
	v_add_f32_e32 v49, 1.0, v49
	v_rcp_f32_e32 v48, v48
	v_rcp_f32_e32 v49, v49
	v_mul_f32_e32 v39, v44, v39
	v_mul_f32_e32 v44, v40, v47
	v_mul_f32_e32 v40, v45, v48
	v_mul_f32_e32 v41, v41, v49
	v_cvt_pk_bf16_f32 v38, v42, v38
	v_cvt_pk_bf16_f32 v39, v39, v40
	v_cvt_pk_bf16_f32 v40, v46, v43
	v_cvt_pk_bf16_f32 v41, v44, v41
	ds_write_b128 v227, v[38:41] offset:64
	ds_read_b128 v[38:41], v3
	ds_read_b128 v[42:45], v3 offset:1152
	s_waitcnt lgkmcnt(1)
	global_store_dwordx4 v[62:63], v[38:41], off offset:2048
	s_waitcnt lgkmcnt(0)
	global_store_dwordx4 v[62:63], v[42:45], off offset:3072
	ds_write_b128 v3, v[158:161]
	ds_write_b128 v3, v[162:165] offset:1152
	ds_read_b128 v[38:41], v227
	ds_read_b128 v[42:45], v227 offset:64
	s_waitcnt lgkmcnt(1)
	v_lshlrev_b32_e32 v46, 16, v38
	v_and_b32_e32 v38, 0xffff0000, v38
	v_lshlrev_b32_e32 v48, 16, v40
	v_fma_f32 v46, v46, s89, v146
	v_fma_f32 v48, v48, s89, v142
	v_fma_f32 v38, v38, s89, v147
	v_med3_f32 v46, v46, s85, v226
	v_med3_f32 v48, v48, s85, v226
	v_med3_f32 v38, v38, s85, v226
	v_exp_f32_e32 v46, v46
	v_exp_f32_e32 v48, v48
	v_exp_f32_e32 v38, v38
	v_and_b32_e32 v40, 0xffff0000, v40
	v_fma_f32 v40, v40, s89, v143
	v_add_f32_e32 v46, 1.0, v46
	v_add_f32_e32 v48, 1.0, v48
	v_add_f32_e32 v38, 1.0, v38
	v_med3_f32 v40, v40, s85, v226
	v_rcp_f32_e32 v46, v46
	v_rcp_f32_e32 v48, v48
	v_rcp_f32_e32 v38, v38
	v_exp_f32_e32 v40, v40
	v_lshlrev_b32_e32 v47, 16, v39
	v_lshlrev_b32_e32 v49, 16, v41
	v_mul_f32_e32 v34, v34, v46
	v_mul_f32_e32 v46, v30, v48
	v_mul_f32_e32 v30, v35, v38
	v_add_f32_e32 v35, 1.0, v40
	v_fma_f32 v38, v47, s89, v148
	v_fma_f32 v40, v49, s89, v144
	v_med3_f32 v38, v38, s85, v226
	v_med3_f32 v40, v40, s85, v226
	v_rcp_f32_e32 v35, v35
	v_exp_f32_e32 v38, v38
	v_exp_f32_e32 v40, v40
	v_and_b32_e32 v39, 0xffff0000, v39
	v_and_b32_e32 v41, 0xffff0000, v41
	v_mul_f32_e32 v35, v31, v35
	v_add_f32_e32 v31, 1.0, v38
	v_add_f32_e32 v38, 1.0, v40
	v_fma_f32 v39, v39, s89, v149
	v_fma_f32 v40, v41, s89, v145
	v_med3_f32 v39, v39, s85, v226
	v_med3_f32 v40, v40, s85, v226
	v_exp_f32_e32 v39, v39
	v_exp_f32_e32 v40, v40
	v_rcp_f32_e32 v31, v31
	v_rcp_f32_e32 v38, v38
	v_add_f32_e32 v39, 1.0, v39
	v_add_f32_e32 v40, 1.0, v40
	v_rcp_f32_e32 v39, v39
	v_rcp_f32_e32 v40, v40
	v_mul_f32_e32 v31, v36, v31
	v_mul_f32_e32 v36, v32, v38
	v_mul_f32_e32 v32, v37, v39
	v_mul_f32_e32 v33, v33, v40
	v_cvt_pk_bf16_f32 v30, v34, v30
	v_cvt_pk_bf16_f32 v31, v31, v32
	v_cvt_pk_bf16_f32 v32, v46, v35
	v_cvt_pk_bf16_f32 v33, v36, v33
	ds_write_b128 v227, v[30:33]
	s_waitcnt lgkmcnt(1)
; __device__ __forceinline__ u32x4 pack8(const f32x4& v0, const f32x4& v1) { u32x4 w; w.x = cvt_pk_bf16(v0[0], v0[1]); w.y = cvt_pk_bf16(v0[2], v0[3]); w.z = cvt_pk_bf16(v1[0], v1[1]); w.w = cvt_pk_bf16(v1[2], v1[3]); return w; }
; #define UNPK0(q_) ((f32x4){bf_lo((q_).x), bf_hi((q_).x), bf_lo((q_).y), bf_hi((q_).y)})
; #define UNPK1(q_) ((f32x4){bf_lo((q_).z), bf_hi((q_).z), bf_lo((q_).w), bf_hi((q_).w)})
;     static __device__ __forceinline__ float eneg(float g) { return __builtin_amdgcn_exp2f(-1.4426950408889634f * fminf(fmaxf(g, -30.f), 30.f)); }
; #define PG8_BAR __builtin_amdgcn_s_barrier()
;     __device__ __forceinline__ void operator()(const f32x4 (&acc)[2][2][4][2], const Unit& u, int wr, int wc, int fr, int fq) const {
;     ...
;         for (int ai = 0; ai < 2; ++ai)
; #pragma unroll
;             for (int m = 0; m < 4; ++m) {
;                 pb.stage(rb[ai][m][0], rb[ai][m][1]); const u32x4 gb0 = pb.get(0), gb1 = pb.get(1);
;                 asm volatile("" ::: "memory");
; #pragma unroll
;                 for (int bj = 0; bj < 2; ++bj) { const u32x4 gb = bj ? gb1 : gb0;
;                     const f32x4 b0 = UNPK0(gb) + bb[bj][0], b1 = UNPK1(gb) + bb[bj][1];
;                     f32x4 v0 = acc[ai][bj][m][0], v1 = acc[ai][bj][m][1];
; #pragma unroll
;                     for (int k = 0; k < 4; ++k) { v0[k] *= __builtin_amdgcn_rcpf(1.0f + eneg(b0[k])); v1[k] *= __builtin_amdgcn_rcpf(1.0f + eneg(b1[k])); }
;                     po.put(bj, pack8(v0, v1)); }
;                 po.flush<false>(ai, m);
;                 asm volatile("" ::: "memory"); }
; template <class Epi, class Sched, bool ALIGN_EPI = false, bool SP2 = false>
; __device__ __forceinline__ void gemm_phase(PG8_LAS unsigned char* lds, const Gemm g, const Sched& S, const Epi& E) {
;     ...
;         if (!has_next) break;
; #pragma unroll
;         for (int a = 0; a < 2; ++a)
; #pragma unroll
;             for (int b = 0; b < 2; ++b)
; #pragma unroll
;                 for (int m = 0; m < 4; ++m)
; #pragma unroll
;                     for (int n = 0; n < 2; ++n) acc[a][b][m][n] = (f32x4){0.f, 0.f, 0.f, 0.f};
;         cur = nxt; cA = nA; cB = nB; ++ui;
;         if constexpr (ALIGN_EPI) { if (wr == 1) PG8_BAR; }
	v_lshlrev_b32_e32 v30, 16, v42
	v_and_b32_e32 v31, 0xffff0000, v42
	v_lshlrev_b32_e32 v34, 16, v44
	v_fma_f32 v30, v30, s89, v138
	v_fma_f32 v34, v34, s89, v134
	v_fma_f32 v31, v31, s89, v139
	v_med3_f32 v30, v30, s85, v226
	v_med3_f32 v34, v34, s85, v226
	v_med3_f32 v31, v31, s85, v226
	v_exp_f32_e32 v30, v30
	v_exp_f32_e32 v34, v34
	v_exp_f32_e32 v31, v31
	v_and_b32_e32 v35, 0xffff0000, v44
	v_add_f32_e32 v30, 1.0, v30
	v_add_f32_e32 v34, 1.0, v34
	v_add_f32_e32 v31, 1.0, v31
	v_fma_f32 v35, v35, s89, v135
	v_rcp_f32_e32 v30, v30
	v_rcp_f32_e32 v34, v34
	v_rcp_f32_e32 v31, v31
	v_med3_f32 v35, v35, s85, v226
	v_exp_f32_e32 v35, v35
	v_lshlrev_b32_e32 v32, 16, v43
	v_lshlrev_b32_e32 v36, 16, v45
	v_mul_f32_e32 v26, v26, v30
	v_mul_f32_e32 v30, v22, v34
	v_mul_f32_e32 v22, v27, v31
	v_fma_f32 v31, v32, s89, v140
	v_fma_f32 v32, v36, s89, v136
	v_add_f32_e32 v27, 1.0, v35
	v_med3_f32 v31, v31, s85, v226
	v_med3_f32 v32, v32, s85, v226
	v_rcp_f32_e32 v27, v27
	v_exp_f32_e32 v31, v31
	v_exp_f32_e32 v32, v32
	v_and_b32_e32 v33, 0xffff0000, v43
	v_and_b32_e32 v37, 0xffff0000, v45
	v_mul_f32_e32 v27, v23, v27
	v_add_f32_e32 v23, 1.0, v31
	v_add_f32_e32 v31, 1.0, v32
	v_fma_f32 v32, v33, s89, v141
	v_fma_f32 v33, v37, s89, v137
	v_med3_f32 v32, v32, s85, v226
	v_med3_f32 v33, v33, s85, v226
	v_exp_f32_e32 v32, v32
	v_exp_f32_e32 v33, v33
	v_rcp_f32_e32 v23, v23
	v_rcp_f32_e32 v31, v31
	v_add_f32_e32 v32, 1.0, v32
	v_add_f32_e32 v33, 1.0, v33
	v_rcp_f32_e32 v32, v32
	v_rcp_f32_e32 v33, v33
	v_mul_f32_e32 v23, v28, v23
	v_mul_f32_e32 v28, v24, v31
	v_mul_f32_e32 v24, v29, v32
	v_mul_f32_e32 v25, v25, v33
	v_cvt_pk_bf16_f32 v22, v26, v22
	v_cvt_pk_bf16_f32 v23, v23, v24
	v_cvt_pk_bf16_f32 v24, v30, v27
	v_cvt_pk_bf16_f32 v25, v28, v25
	ds_write_b128 v227, v[22:25] offset:64
	ds_read_b128 v[22:25], v3
	ds_read_b128 v[26:29], v3 offset:1152
	s_waitcnt lgkmcnt(1)
	global_store_dwordx4 v[4:5], v[22:25], off
	s_waitcnt lgkmcnt(0)
	global_store_dwordx4 v[4:5], v[26:29], off offset:1024
	ds_write_b128 v3, v[150:153]
	ds_write_b128 v3, v[154:157] offset:1152
	ds_read_b128 v[22:25], v227
	ds_read_b128 v[26:29], v227 offset:64
	s_waitcnt lgkmcnt(1)
	v_lshlrev_b32_e32 v30, 16, v22
	v_and_b32_e32 v22, 0xffff0000, v22
	v_lshlrev_b32_e32 v32, 16, v24
	v_fma_f32 v30, v30, s89, v146
	v_fma_f32 v32, v32, s89, v142
	v_fma_f32 v22, v22, s89, v147
	v_med3_f32 v30, v30, s85, v226
	v_med3_f32 v32, v32, s85, v226
	v_med3_f32 v22, v22, s85, v226
	v_exp_f32_e32 v30, v30
	v_exp_f32_e32 v32, v32
	v_exp_f32_e32 v22, v22
	v_and_b32_e32 v24, 0xffff0000, v24
	v_fma_f32 v24, v24, s89, v143
	v_add_f32_e32 v30, 1.0, v30
	v_add_f32_e32 v32, 1.0, v32
	v_add_f32_e32 v22, 1.0, v22
	v_med3_f32 v24, v24, s85, v226
	v_rcp_f32_e32 v30, v30
	v_rcp_f32_e32 v32, v32
	v_rcp_f32_e32 v22, v22
	v_exp_f32_e32 v24, v24
	v_lshlrev_b32_e32 v31, 16, v23
	v_lshlrev_b32_e32 v33, 16, v25
	v_mul_f32_e32 v18, v18, v30
	v_mul_f32_e32 v30, v14, v32
	v_mul_f32_e32 v14, v19, v22
	v_add_f32_e32 v19, 1.0, v24
	v_fma_f32 v22, v31, s89, v148
	v_fma_f32 v24, v33, s89, v144
	v_med3_f32 v22, v22, s85, v226
	v_med3_f32 v24, v24, s85, v226
	v_rcp_f32_e32 v19, v19
	v_exp_f32_e32 v22, v22
	v_exp_f32_e32 v24, v24
	v_and_b32_e32 v23, 0xffff0000, v23
	v_and_b32_e32 v25, 0xffff0000, v25
	v_mul_f32_e32 v19, v15, v19
	v_add_f32_e32 v15, 1.0, v22
	v_add_f32_e32 v22, 1.0, v24
	v_fma_f32 v23, v23, s89, v149
	v_fma_f32 v24, v25, s89, v145
	v_med3_f32 v23, v23, s85, v226
	v_med3_f32 v24, v24, s85, v226
	v_exp_f32_e32 v23, v23
	v_exp_f32_e32 v24, v24
	v_rcp_f32_e32 v15, v15
	v_rcp_f32_e32 v22, v22
	v_add_f32_e32 v23, 1.0, v23
	v_add_f32_e32 v24, 1.0, v24
	v_rcp_f32_e32 v23, v23
	v_rcp_f32_e32 v24, v24
	v_mul_f32_e32 v15, v20, v15
	v_mul_f32_e32 v20, v16, v22
	v_mul_f32_e32 v16, v21, v23
	v_mul_f32_e32 v17, v17, v24
	v_cvt_pk_bf16_f32 v14, v18, v14
	v_cvt_pk_bf16_f32 v15, v15, v16
	v_cvt_pk_bf16_f32 v16, v30, v19
	v_cvt_pk_bf16_f32 v17, v20, v17
	ds_write_b128 v227, v[14:17]
	s_waitcnt lgkmcnt(1)
	v_lshlrev_b32_e32 v14, 16, v26
	v_and_b32_e32 v15, 0xffff0000, v26
	v_lshlrev_b32_e32 v18, 16, v28
	v_fma_f32 v14, v14, s89, v138
	v_fma_f32 v18, v18, s89, v134
	v_fma_f32 v15, v15, s89, v139
	v_med3_f32 v14, v14, s85, v226
	v_med3_f32 v18, v18, s85, v226
	v_med3_f32 v15, v15, s85, v226
	v_exp_f32_e32 v14, v14
	v_exp_f32_e32 v18, v18
	v_exp_f32_e32 v15, v15
	v_and_b32_e32 v19, 0xffff0000, v28
	v_add_f32_e32 v14, 1.0, v14
	v_add_f32_e32 v18, 1.0, v18
	v_add_f32_e32 v15, 1.0, v15
	v_fma_f32 v19, v19, s89, v135
	v_rcp_f32_e32 v14, v14
	v_rcp_f32_e32 v18, v18
	v_rcp_f32_e32 v15, v15
	v_med3_f32 v19, v19, s85, v226
	v_exp_f32_e32 v19, v19
	v_lshlrev_b32_e32 v16, 16, v27
	v_lshlrev_b32_e32 v20, 16, v29
	v_mul_f32_e32 v10, v10, v14
	v_mul_f32_e32 v14, v6, v18
	v_mul_f32_e32 v6, v11, v15
	v_fma_f32 v15, v16, s89, v140
	v_fma_f32 v16, v20, s89, v136
	v_add_f32_e32 v11, 1.0, v19
	v_med3_f32 v15, v15, s85, v226
	v_med3_f32 v16, v16, s85, v226
	v_rcp_f32_e32 v11, v11
	v_exp_f32_e32 v15, v15
	v_exp_f32_e32 v16, v16
	v_and_b32_e32 v17, 0xffff0000, v27
	v_and_b32_e32 v21, 0xffff0000, v29
	v_mul_f32_e32 v11, v7, v11
	v_add_f32_e32 v7, 1.0, v15
	v_add_f32_e32 v15, 1.0, v16
	v_fma_f32 v16, v17, s89, v141
	v_fma_f32 v17, v21, s89, v137
	v_med3_f32 v16, v16, s85, v226
	v_med3_f32 v17, v17, s85, v226
	v_exp_f32_e32 v16, v16
	v_exp_f32_e32 v17, v17
	v_rcp_f32_e32 v7, v7
	v_rcp_f32_e32 v15, v15
	v_add_f32_e32 v16, 1.0, v16
	v_add_f32_e32 v17, 1.0, v17
	v_rcp_f32_e32 v16, v16
	v_rcp_f32_e32 v17, v17
	v_mul_f32_e32 v7, v12, v7
	v_mul_f32_e32 v12, v8, v15
	v_mul_f32_e32 v8, v13, v16
	v_mul_f32_e32 v9, v9, v17
	v_cvt_pk_bf16_f32 v6, v10, v6
	v_cvt_pk_bf16_f32 v7, v7, v8
	v_cvt_pk_bf16_f32 v8, v14, v11
	v_cvt_pk_bf16_f32 v9, v12, v9
	ds_write_b128 v227, v[6:9] offset:64
	ds_read_b128 v[6:9], v3
	ds_read_b128 v[10:13], v3 offset:1152
	s_waitcnt lgkmcnt(1)
	global_store_dwordx4 v[4:5], v[6:9], off offset:2048
	s_waitcnt lgkmcnt(0)
	global_store_dwordx4 v[4:5], v[10:13], off offset:3072
	s_cbranch_vccnz .LBB0_372
	s_andn2_b64 vcc, exec, s[10:11]
	s_cbranch_vccnz .LBB0_371
	s_barrier
	s_branch .LBB0_371
